# sg_item part1: 64 ushort loads batched into one round trip (on reversed N=1024 order + trimmed K-loop DMA)
# speedup vs baseline: 1.0050x; 1.0050x over previous
; __device__ __forceinline__ void sg_item(int l, int chunk, LAS unsigned char* lds, const bf16_t* UB, const bf16_t* V2T, bf16_t* YC1, const bf16_t* Wb,
;                                         const float* sg_ln_g, const float* sg_ln_b, const float* sg_b, int lane, int wave) {
;     ...
;         const int th = wave & 1, cq = wave >> 1, s = 64 * th + lane;
;         const bf16_t* src = V2T + ((size_t)b * BW + 64 * cq) * SEQ + pos0;
;         float v[64]; float sum = 0.f, sq = 0.f;
; #pragma unroll
;         for (int cb = 0; cb < 64; cb += 8) {
;             unsigned raw[8]; const void* pp[8];
; #pragma unroll
;             for (int j = 0; j < 8; ++j) pp[j] = src + (size_t)(cb + j) * SEQ;
;             ld_u16_s8(raw, (unsigned)s * 2u, pp);
; #pragma unroll
;             for (int j = 0; j < 8; ++j) v[cb + j] = __uint_as_float(raw[j] << 16);
;         }
.LBB0_79:
	s_and_b32 s12, s88, 0xf80
	s_and_b32 s1, s85, 0x7ffff
	s_and_b32 s0, s84, 0xffffff00
	s_add_u32 s0, s0, s15
	s_addc_u32 s1, s1, s46
	s_lshl_b64 s[0:1], s[0:1], 13
	s_add_u32 s0, s2, s0
	s_addc_u32 s1, s3, s1
	s_lshl_b32 s12, s12, 1
	s_add_u32 s0, s0, s12
	s_addc_u32 s1, s1, 0
	s_mov_b64 s[48:49], s[0:1]
	s_nop 4
	global_load_ushort v132, v149, s[48:49]
	s_add_u32 s48, s48, 0x2000
	s_addc_u32 s49, s49, 0
	global_load_ushort v133, v149, s[48:49]
	s_add_u32 s48, s48, 0x2000
	s_addc_u32 s49, s49, 0
	global_load_ushort v130, v149, s[48:49]
	s_add_u32 s48, s48, 0x2000
	s_addc_u32 s49, s49, 0
	global_load_ushort v128, v149, s[48:49]
	s_add_u32 s48, s48, 0x2000
	s_addc_u32 s49, s49, 0
	global_load_ushort v126, v149, s[48:49]
	s_add_u32 s48, s48, 0x2000
	s_addc_u32 s49, s49, 0
	global_load_ushort v124, v149, s[48:49]
	s_add_u32 s48, s48, 0x2000
	s_addc_u32 s49, s49, 0
	global_load_ushort v120, v149, s[48:49]
	s_add_u32 s48, s48, 0x2000
	s_addc_u32 s49, s49, 0
	global_load_ushort v116, v149, s[48:49]
	s_add_u32 s48, s48, 0x2000
	s_addc_u32 s49, s49, 0
	global_load_ushort v122, v149, s[48:49]
	s_add_u32 s48, s48, 0x2000
	s_addc_u32 s49, s49, 0
	global_load_ushort v118, v149, s[48:49]
	s_add_u32 s48, s48, 0x2000
	s_addc_u32 s49, s49, 0
	global_load_ushort v114, v149, s[48:49]
	s_add_u32 s48, s48, 0x2000
	s_addc_u32 s49, s49, 0
	global_load_ushort v112, v149, s[48:49]
	s_add_u32 s48, s48, 0x2000
	s_addc_u32 s49, s49, 0
	global_load_ushort v110, v149, s[48:49]
	s_add_u32 s48, s48, 0x2000
	s_addc_u32 s49, s49, 0
	global_load_ushort v108, v149, s[48:49]
	s_add_u32 s48, s48, 0x2000
	s_addc_u32 s49, s49, 0
	global_load_ushort v104, v149, s[48:49]
	s_add_u32 s48, s48, 0x2000
	s_addc_u32 s49, s49, 0
	global_load_ushort v100, v149, s[48:49]
	s_add_u32 s48, s48, 0x2000
	s_addc_u32 s49, s49, 0
	global_load_ushort v106, v149, s[48:49]
	s_add_u32 s48, s48, 0x2000
	s_addc_u32 s49, s49, 0
	global_load_ushort v102, v149, s[48:49]
	s_add_u32 s48, s48, 0x2000
	s_addc_u32 s49, s49, 0
	global_load_ushort v98, v149, s[48:49]
	s_add_u32 s48, s48, 0x2000
	s_addc_u32 s49, s49, 0
	global_load_ushort v96, v149, s[48:49]
	s_add_u32 s48, s48, 0x2000
	s_addc_u32 s49, s49, 0
	global_load_ushort v94, v149, s[48:49]
	s_add_u32 s48, s48, 0x2000
	s_addc_u32 s49, s49, 0
	global_load_ushort v92, v149, s[48:49]
	s_add_u32 s48, s48, 0x2000
	s_addc_u32 s49, s49, 0
	global_load_ushort v88, v149, s[48:49]
	s_add_u32 s48, s48, 0x2000
	s_addc_u32 s49, s49, 0
	global_load_ushort v84, v149, s[48:49]
	s_add_u32 s48, s48, 0x2000
	s_addc_u32 s49, s49, 0
	global_load_ushort v90, v149, s[48:49]
	s_add_u32 s48, s48, 0x2000
	s_addc_u32 s49, s49, 0
	global_load_ushort v86, v149, s[48:49]
	s_add_u32 s48, s48, 0x2000
	s_addc_u32 s49, s49, 0
	global_load_ushort v82, v149, s[48:49]
	s_add_u32 s48, s48, 0x2000
	s_addc_u32 s49, s49, 0
	global_load_ushort v80, v149, s[48:49]
	s_add_u32 s48, s48, 0x2000
	s_addc_u32 s49, s49, 0
	global_load_ushort v78, v149, s[48:49]
	s_add_u32 s48, s48, 0x2000
	s_addc_u32 s49, s49, 0
	global_load_ushort v76, v149, s[48:49]
	s_add_u32 s48, s48, 0x2000
	s_addc_u32 s49, s49, 0
	global_load_ushort v72, v149, s[48:49]
	s_add_u32 s48, s48, 0x2000
	s_addc_u32 s49, s49, 0
	global_load_ushort v60, v149, s[48:49]
	s_add_u32 s48, s48, 0x2000
	s_addc_u32 s49, s49, 0
	global_load_ushort v74, v149, s[48:49]
	s_add_u32 s48, s48, 0x2000
	s_addc_u32 s49, s49, 0
	global_load_ushort v62, v149, s[48:49]
	s_add_u32 s48, s48, 0x2000
	s_addc_u32 s49, s49, 0
	global_load_ushort v58, v149, s[48:49]
	s_add_u32 s48, s48, 0x2000
	s_addc_u32 s49, s49, 0
	global_load_ushort v56, v149, s[48:49]
	s_add_u32 s48, s48, 0x2000
	s_addc_u32 s49, s49, 0
	global_load_ushort v54, v149, s[48:49]
	s_add_u32 s48, s48, 0x2000
	s_addc_u32 s49, s49, 0
	global_load_ushort v52, v149, s[48:49]
	s_add_u32 s48, s48, 0x2000
	s_addc_u32 s49, s49, 0
	global_load_ushort v48, v149, s[48:49]
	s_add_u32 s48, s48, 0x2000
	s_addc_u32 s49, s49, 0
	global_load_ushort v44, v149, s[48:49]
	s_add_u32 s48, s48, 0x2000
	s_addc_u32 s49, s49, 0
	global_load_ushort v50, v149, s[48:49]
	s_add_u32 s48, s48, 0x2000
	s_addc_u32 s49, s49, 0
	global_load_ushort v46, v149, s[48:49]
	s_add_u32 s48, s48, 0x2000
	s_addc_u32 s49, s49, 0
	global_load_ushort v42, v149, s[48:49]
	s_add_u32 s48, s48, 0x2000
	s_addc_u32 s49, s49, 0
	global_load_ushort v40, v149, s[48:49]
	s_add_u32 s48, s48, 0x2000
	s_addc_u32 s49, s49, 0
	global_load_ushort v38, v149, s[48:49]
	s_add_u32 s48, s48, 0x2000
	s_addc_u32 s49, s49, 0
	global_load_ushort v36, v149, s[48:49]
	s_add_u32 s48, s48, 0x2000
	s_addc_u32 s49, s49, 0
	global_load_ushort v32, v149, s[48:49]
	s_add_u32 s48, s48, 0x2000
	s_addc_u32 s49, s49, 0
	global_load_ushort v28, v149, s[48:49]
	s_add_u32 s48, s48, 0x2000
	s_addc_u32 s49, s49, 0
	global_load_ushort v34, v149, s[48:49]
	s_add_u32 s48, s48, 0x2000
	s_addc_u32 s49, s49, 0
	global_load_ushort v30, v149, s[48:49]
	s_add_u32 s48, s48, 0x2000
	s_addc_u32 s49, s49, 0
	global_load_ushort v26, v149, s[48:49]
	s_add_u32 s48, s48, 0x2000
	s_addc_u32 s49, s49, 0
	global_load_ushort v24, v149, s[48:49]
	s_add_u32 s48, s48, 0x2000
	s_addc_u32 s49, s49, 0
	global_load_ushort v22, v149, s[48:49]
	s_add_u32 s48, s48, 0x2000
	s_addc_u32 s49, s49, 0
	global_load_ushort v20, v149, s[48:49]
	s_add_u32 s48, s48, 0x2000
	s_addc_u32 s49, s49, 0
	global_load_ushort v16, v149, s[48:49]
	s_add_u32 s48, s48, 0x2000
	s_addc_u32 s49, s49, 0
	global_load_ushort v12, v149, s[48:49]
	s_add_u32 s48, s48, 0x2000
	s_addc_u32 s49, s49, 0
	global_load_ushort v18, v149, s[48:49]
	s_add_u32 s48, s48, 0x2000
	s_addc_u32 s49, s49, 0
	global_load_ushort v14, v149, s[48:49]
	s_add_u32 s48, s48, 0x2000
	s_addc_u32 s49, s49, 0
	global_load_ushort v10, v149, s[48:49]
	s_add_u32 s48, s48, 0x2000
	s_addc_u32 s49, s49, 0
	global_load_ushort v8, v149, s[48:49]
	s_add_u32 s48, s48, 0x2000
	s_addc_u32 s49, s49, 0
	global_load_ushort v6, v149, s[48:49]
	s_add_u32 s48, s48, 0x2000
	s_addc_u32 s49, s49, 0
	global_load_ushort v4, v149, s[48:49]
	s_add_u32 s48, s48, 0x2000
	s_addc_u32 s49, s49, 0
	global_load_ushort v2, v149, s[48:49]
	s_add_u32 s48, s48, 0x2000
	s_addc_u32 s49, s49, 0
	global_load_ushort v0, v149, s[48:49]
	s_waitcnt vmcnt(0)
; __device__ __forceinline__ void sg_item(int l, int chunk, LAS unsigned char* lds, const bf16_t* UB, const bf16_t* V2T, bf16_t* YC1, const bf16_t* Wb,
;                                         const float* sg_ln_g, const float* sg_ln_b, const float* sg_b, int lane, int wave) {
;     ...
;             for (int j = 0; j < 8; ++j) v[cb + j] = __uint_as_float(raw[j] << 16);
;         }
; #pragma unroll
;         for (int c = 0; c < 64; ++c) { sum += v[c]; sq += v[c] * v[c]; }
	v_lshlrev_b32_e32 v132, 16, v132
	v_lshlrev_b32_e32 v133, 16, v133
	v_lshlrev_b32_e32 v130, 16, v130
	v_lshlrev_b32_e32 v128, 16, v128
	v_lshlrev_b32_e32 v126, 16, v126
	v_lshlrev_b32_e32 v124, 16, v124
	v_lshlrev_b32_e32 v120, 16, v120
	v_lshlrev_b32_e32 v116, 16, v116
	v_lshlrev_b32_e32 v122, 16, v122
	v_lshlrev_b32_e32 v118, 16, v118
	v_lshlrev_b32_e32 v114, 16, v114
	v_lshlrev_b32_e32 v112, 16, v112
	v_lshlrev_b32_e32 v110, 16, v110
	v_lshlrev_b32_e32 v108, 16, v108
	v_lshlrev_b32_e32 v104, 16, v104
	v_lshlrev_b32_e32 v100, 16, v100
	v_lshlrev_b32_e32 v106, 16, v106
	v_lshlrev_b32_e32 v102, 16, v102
	v_lshlrev_b32_e32 v98, 16, v98
	v_lshlrev_b32_e32 v96, 16, v96
	v_lshlrev_b32_e32 v94, 16, v94
	v_lshlrev_b32_e32 v92, 16, v92
	v_lshlrev_b32_e32 v88, 16, v88
	v_lshlrev_b32_e32 v84, 16, v84
	v_lshlrev_b32_e32 v90, 16, v90
	v_lshlrev_b32_e32 v86, 16, v86
	v_lshlrev_b32_e32 v82, 16, v82
	v_lshlrev_b32_e32 v80, 16, v80
	v_lshlrev_b32_e32 v78, 16, v78
	v_lshlrev_b32_e32 v76, 16, v76
	v_lshlrev_b32_e32 v72, 16, v72
	v_lshlrev_b32_e32 v60, 16, v60
	v_lshlrev_b32_e32 v74, 16, v74
	v_lshlrev_b32_e32 v62, 16, v62
	v_lshlrev_b32_e32 v58, 16, v58
	v_lshlrev_b32_e32 v56, 16, v56
	v_lshlrev_b32_e32 v54, 16, v54
	v_lshlrev_b32_e32 v52, 16, v52
	v_lshlrev_b32_e32 v48, 16, v48
	v_lshlrev_b32_e32 v44, 16, v44
	v_lshlrev_b32_e32 v50, 16, v50
	v_lshlrev_b32_e32 v46, 16, v46
	v_lshlrev_b32_e32 v42, 16, v42
	v_lshlrev_b32_e32 v40, 16, v40
	v_lshlrev_b32_e32 v38, 16, v38
	v_lshlrev_b32_e32 v36, 16, v36
	v_lshlrev_b32_e32 v32, 16, v32
	v_lshlrev_b32_e32 v28, 16, v28
	v_lshlrev_b32_e32 v34, 16, v34
	v_lshlrev_b32_e32 v30, 16, v30
	v_lshlrev_b32_e32 v26, 16, v26
	v_lshlrev_b32_e32 v24, 16, v24
	v_lshlrev_b32_e32 v22, 16, v22
	v_lshlrev_b32_e32 v20, 16, v20
	v_lshlrev_b32_e32 v16, 16, v16
	v_lshlrev_b32_e32 v12, 16, v12
	v_lshlrev_b32_e32 v18, 16, v18
	v_lshlrev_b32_e32 v14, 16, v14
	v_lshlrev_b32_e32 v10, 16, v10
	v_lshlrev_b32_e32 v8, 16, v8
	v_lshlrev_b32_e32 v6, 16, v6
	v_lshlrev_b32_e32 v4, 16, v4
	v_lshlrev_b32_e32 v2, 16, v2
	v_lshlrev_b32_e32 v0, 16, v0
	v_mul_f32_e32 v221, v132, v132
	v_fmac_f32_e32 v221, v133, v133
	v_add_f32_e32 v220, v132, v133
	v_mul_f32_e32 v131, v130, v130
	v_pk_add_f32 v[220:221], v[220:221], v[130:131]
	v_mul_f32_e32 v129, v128, v128
	v_pk_add_f32 v[220:221], v[220:221], v[128:129]
	v_mul_f32_e32 v127, v126, v126
	v_pk_add_f32 v[220:221], v[220:221], v[126:127]
	v_mul_f32_e32 v125, v124, v124
	v_pk_add_f32 v[220:221], v[220:221], v[124:125]
	v_mul_f32_e32 v121, v120, v120
	v_pk_add_f32 v[220:221], v[220:221], v[120:121]
	v_mul_f32_e32 v117, v116, v116
	v_pk_add_f32 v[220:221], v[220:221], v[116:117]
	v_mul_f32_e32 v123, v122, v122
	v_pk_add_f32 v[220:221], v[220:221], v[122:123]
	v_mul_f32_e32 v119, v118, v118
	v_pk_add_f32 v[220:221], v[220:221], v[118:119]
	v_mul_f32_e32 v115, v114, v114
	v_pk_add_f32 v[220:221], v[220:221], v[114:115]
	v_mul_f32_e32 v113, v112, v112
	v_pk_add_f32 v[220:221], v[220:221], v[112:113]
	v_mul_f32_e32 v111, v110, v110
	v_pk_add_f32 v[220:221], v[220:221], v[110:111]
	v_mul_f32_e32 v109, v108, v108
	v_pk_add_f32 v[220:221], v[220:221], v[108:109]
	v_mul_f32_e32 v105, v104, v104
	v_pk_add_f32 v[220:221], v[220:221], v[104:105]
	v_mul_f32_e32 v101, v100, v100
	v_pk_add_f32 v[220:221], v[220:221], v[100:101]
	v_mul_f32_e32 v107, v106, v106
	v_pk_add_f32 v[220:221], v[220:221], v[106:107]
	v_mul_f32_e32 v103, v102, v102
	v_pk_add_f32 v[220:221], v[220:221], v[102:103]
	v_mul_f32_e32 v99, v98, v98
	v_pk_add_f32 v[220:221], v[220:221], v[98:99]
	v_mul_f32_e32 v97, v96, v96
	v_pk_add_f32 v[220:221], v[220:221], v[96:97]
	v_mul_f32_e32 v95, v94, v94
	v_pk_add_f32 v[220:221], v[220:221], v[94:95]
	v_mul_f32_e32 v93, v92, v92
	v_pk_add_f32 v[220:221], v[220:221], v[92:93]
	v_mul_f32_e32 v89, v88, v88
	v_pk_add_f32 v[220:221], v[220:221], v[88:89]
	v_mul_f32_e32 v85, v84, v84
	v_pk_add_f32 v[220:221], v[220:221], v[84:85]
	v_mul_f32_e32 v91, v90, v90
	v_pk_add_f32 v[220:221], v[220:221], v[90:91]
	v_mul_f32_e32 v87, v86, v86
	v_pk_add_f32 v[220:221], v[220:221], v[86:87]
	v_mul_f32_e32 v83, v82, v82
	v_pk_add_f32 v[220:221], v[220:221], v[82:83]
	v_mul_f32_e32 v81, v80, v80
	v_pk_add_f32 v[220:221], v[220:221], v[80:81]
	v_mul_f32_e32 v79, v78, v78
	v_pk_add_f32 v[220:221], v[220:221], v[78:79]
	v_mul_f32_e32 v77, v76, v76
	v_pk_add_f32 v[220:221], v[220:221], v[76:77]
	v_mul_f32_e32 v73, v72, v72
	v_pk_add_f32 v[220:221], v[220:221], v[72:73]
	v_mul_f32_e32 v61, v60, v60
	v_pk_add_f32 v[220:221], v[220:221], v[60:61]
	v_mul_f32_e32 v75, v74, v74
	v_pk_add_f32 v[220:221], v[220:221], v[74:75]
	v_mul_f32_e32 v63, v62, v62
	v_pk_add_f32 v[220:221], v[220:221], v[62:63]
	v_mul_f32_e32 v59, v58, v58
	v_pk_add_f32 v[220:221], v[220:221], v[58:59]
	v_mul_f32_e32 v57, v56, v56
	v_pk_add_f32 v[220:221], v[220:221], v[56:57]
	v_mul_f32_e32 v55, v54, v54
	v_pk_add_f32 v[220:221], v[220:221], v[54:55]
	v_mul_f32_e32 v53, v52, v52
	v_pk_add_f32 v[220:221], v[220:221], v[52:53]
	v_mul_f32_e32 v49, v48, v48
	v_pk_add_f32 v[220:221], v[220:221], v[48:49]
	v_mul_f32_e32 v45, v44, v44
	v_pk_add_f32 v[220:221], v[220:221], v[44:45]
	v_mul_f32_e32 v51, v50, v50
	v_pk_add_f32 v[220:221], v[220:221], v[50:51]
	v_mul_f32_e32 v47, v46, v46
	v_pk_add_f32 v[220:221], v[220:221], v[46:47]
	v_mul_f32_e32 v43, v42, v42
	v_pk_add_f32 v[220:221], v[220:221], v[42:43]
	v_mul_f32_e32 v41, v40, v40
	v_pk_add_f32 v[220:221], v[220:221], v[40:41]
	v_mul_f32_e32 v39, v38, v38
	v_pk_add_f32 v[220:221], v[220:221], v[38:39]
	v_mul_f32_e32 v37, v36, v36
	v_pk_add_f32 v[220:221], v[220:221], v[36:37]
	v_mul_f32_e32 v33, v32, v32
; __device__ __forceinline__ bf16_t f2bf(float f) { return (bf16_t)(cvt_pk_bf16(f, f) & 0xffffu); }
; __device__ __forceinline__ float ln_eps_s() { float e = LN_EPS; asm volatile("" : "+s"(e)); return e; }
; __device__ __forceinline__ void sg_item(int l, int chunk, LAS unsigned char* lds, const bf16_t* UB, const bf16_t* V2T, bf16_t* YC1, const bf16_t* Wb,
;                                         const float* sg_ln_g, const float* sg_ln_b, const float* sg_b, int lane, int wave) {
;     ...
;         for (int c = 0; c < 64; ++c) { sum += v[c]; sq += v[c] * v[c]; }
;         part[(cq * 128 + s) * 2] = sum; part[(cq * 128 + s) * 2 + 1] = sq;
;         const float gl = sg_ln_g[l * BW + 64 * cq + lane], bl = sg_ln_b[l * BW + 64 * cq + lane];
;         __syncthreads();
;         float ts = 0.f, tq = 0.f;
; #pragma unroll
;         for (int k = 0; k < 4; ++k) { ts += part[(k * 128 + s) * 2]; tq += part[(k * 128 + s) * 2 + 1]; }
;         const float mean = ts * (1.f / BW), var = fmaxf(tq * (1.f / BW) - mean * mean, 0.f), rstd = __builtin_amdgcn_rsqf(var + ln_eps_s());
; #pragma unroll
;         for (int c = 0; c < 64; ++c) {
;             const float gc = __uint_as_float(__builtin_amdgcn_readlane(__float_as_uint(gl), c)), bc = __uint_as_float(__builtin_amdgcn_readlane(__float_as_uint(bl), c));
;             vT[(64 * cq + c) * VS + s] = f2bf((v[c] - mean) * rstd * gc + bc);
	v_pk_add_f32 v[220:221], v[220:221], v[32:33]
	v_mul_f32_e32 v29, v28, v28
	v_pk_add_f32 v[220:221], v[220:221], v[28:29]
	v_mul_f32_e32 v35, v34, v34
	v_pk_add_f32 v[220:221], v[220:221], v[34:35]
	v_mul_f32_e32 v31, v30, v30
	v_pk_add_f32 v[220:221], v[220:221], v[30:31]
	v_mul_f32_e32 v27, v26, v26
	v_pk_add_f32 v[220:221], v[220:221], v[26:27]
	v_mul_f32_e32 v25, v24, v24
	v_pk_add_f32 v[220:221], v[220:221], v[24:25]
	v_mul_f32_e32 v23, v22, v22
	v_pk_add_f32 v[220:221], v[220:221], v[22:23]
	v_mul_f32_e32 v21, v20, v20
	v_pk_add_f32 v[220:221], v[220:221], v[20:21]
	v_mul_f32_e32 v17, v16, v16
	v_pk_add_f32 v[220:221], v[220:221], v[16:17]
	v_mul_f32_e32 v13, v12, v12
	v_pk_add_f32 v[220:221], v[220:221], v[12:13]
	v_mul_f32_e32 v19, v18, v18
	v_pk_add_f32 v[220:221], v[220:221], v[18:19]
	v_mul_f32_e32 v15, v14, v14
	v_pk_add_f32 v[220:221], v[220:221], v[14:15]
	v_mul_f32_e32 v11, v10, v10
	v_pk_add_f32 v[220:221], v[220:221], v[10:11]
	v_mul_f32_e32 v9, v8, v8
	v_pk_add_f32 v[220:221], v[220:221], v[8:9]
	v_mul_f32_e32 v7, v6, v6
	v_pk_add_f32 v[220:221], v[220:221], v[6:7]
	v_mul_f32_e32 v5, v4, v4
	v_pk_add_f32 v[220:221], v[220:221], v[4:5]
	v_mul_f32_e32 v3, v2, v2
	v_pk_add_f32 v[220:221], v[220:221], v[2:3]
	v_mul_f32_e32 v1, v0, v0
	v_pk_add_f32 v[220:221], v[220:221], v[0:1]
	s_mov_b32 s0, 0x3b800000
	ds_write_b64 v150, v[220:221]
	global_load_dword v1, v[64:65], off
	global_load_dword v3, v[66:67], off
	s_waitcnt lgkmcnt(0)
	s_barrier
	ds_read2st64_b64 v[220:223], v151 offset1:2
	s_add_u32 s48, s4, s80
	s_addc_u32 s49, s5, s81
	s_mov_b32 s12, 0xb400000
	s_waitcnt lgkmcnt(0)
	v_add_f32_e32 v5, 0, v220
	v_add_f32_e32 v7, 0, v221
	v_add_f32_e32 v5, v5, v222
	v_add_f32_e32 v7, v7, v223
	ds_read2st64_b64 v[220:223], v151 offset0:4 offset1:6
	s_waitcnt lgkmcnt(0)
	v_add_f32_e32 v5, v5, v220
	v_add_f32_e32 v5, v5, v222
	v_add_f32_e32 v7, v7, v221
	v_mul_f32_e32 v9, 0x3b800000, v5
	v_add_f32_e32 v7, v7, v223
	v_mul_f32_e32 v9, v9, v9
	v_fma_f32 v7, v7, s0, -v9
	v_max_f32_e32 v7, 0, v7
	s_mov_b32 s0, 0x3727c5ac
	v_fmac_f32_e32 v132, 0xbb800000, v5
	v_add_f32_e32 v7, s0, v7
	v_rsq_f32_e32 v7, v7
	v_fmac_f32_e32 v133, 0xbb800000, v5
	v_fmac_f32_e32 v130, 0xbb800000, v5
	v_fmac_f32_e32 v128, 0xbb800000, v5
	v_mul_f32_e32 v9, v132, v7
	v_fmac_f32_e32 v126, 0xbb800000, v5
	v_fmac_f32_e32 v124, 0xbb800000, v5
	v_fmac_f32_e32 v120, 0xbb800000, v5
	v_fmac_f32_e32 v116, 0xbb800000, v5
	v_fmac_f32_e32 v122, 0xbb800000, v5
	v_fmac_f32_e32 v118, 0xbb800000, v5
	v_fmac_f32_e32 v114, 0xbb800000, v5
	v_fmac_f32_e32 v112, 0xbb800000, v5
	v_fmac_f32_e32 v110, 0xbb800000, v5
	v_fmac_f32_e32 v108, 0xbb800000, v5
	v_fmac_f32_e32 v104, 0xbb800000, v5
	v_fmac_f32_e32 v100, 0xbb800000, v5
	v_fmac_f32_e32 v106, 0xbb800000, v5
	v_fmac_f32_e32 v102, 0xbb800000, v5
	v_fmac_f32_e32 v98, 0xbb800000, v5
	v_fmac_f32_e32 v96, 0xbb800000, v5
	v_fmac_f32_e32 v94, 0xbb800000, v5
	v_fmac_f32_e32 v92, 0xbb800000, v5
	v_fmac_f32_e32 v88, 0xbb800000, v5
	v_fmac_f32_e32 v84, 0xbb800000, v5
	v_fmac_f32_e32 v90, 0xbb800000, v5
	v_fmac_f32_e32 v86, 0xbb800000, v5
	v_fmac_f32_e32 v82, 0xbb800000, v5
	v_fmac_f32_e32 v80, 0xbb800000, v5
	v_fmac_f32_e32 v78, 0xbb800000, v5
	v_fmac_f32_e32 v76, 0xbb800000, v5
	v_fmac_f32_e32 v72, 0xbb800000, v5
	v_fmac_f32_e32 v60, 0xbb800000, v5
	v_fmac_f32_e32 v74, 0xbb800000, v5
	v_fmac_f32_e32 v62, 0xbb800000, v5
	v_fmac_f32_e32 v58, 0xbb800000, v5
	v_fmac_f32_e32 v56, 0xbb800000, v5
	v_fmac_f32_e32 v54, 0xbb800000, v5
	v_fmac_f32_e32 v52, 0xbb800000, v5
	v_fmac_f32_e32 v48, 0xbb800000, v5
	v_fmac_f32_e32 v44, 0xbb800000, v5
	v_fmac_f32_e32 v50, 0xbb800000, v5
	v_fmac_f32_e32 v46, 0xbb800000, v5
	v_fmac_f32_e32 v42, 0xbb800000, v5
	v_fmac_f32_e32 v40, 0xbb800000, v5
	v_fmac_f32_e32 v38, 0xbb800000, v5
	v_fmac_f32_e32 v36, 0xbb800000, v5
	v_fmac_f32_e32 v32, 0xbb800000, v5
	v_fmac_f32_e32 v28, 0xbb800000, v5
	s_waitcnt vmcnt(1)
	v_readlane_b32 s0, v1, 0
	s_waitcnt vmcnt(0)
	v_readlane_b32 s1, v3, 0
	v_fmac_f32_e32 v34, 0xbb800000, v5
	v_fmac_f32_e32 v30, 0xbb800000, v5
	v_mov_b32_e32 v11, s1
	v_fmac_f32_e32 v11, s0, v9
	v_cvt_pk_bf16_f32 v9, v11, v11
	v_readlane_b32 s1, v3, 1
	ds_write_b16 v202, v9
	v_readlane_b32 s0, v1, 1
	v_mul_f32_e32 v9, v133, v7
	v_mov_b32_e32 v11, s1
	v_fmac_f32_e32 v11, s0, v9
	v_cvt_pk_bf16_f32 v9, v11, v11
	v_readlane_b32 s1, v3, 2
	ds_write_b16 v202, v9 offset:272
	v_readlane_b32 s0, v1, 2
	v_mul_f32_e32 v9, v130, v7
	v_mov_b32_e32 v11, s1
	v_fmac_f32_e32 v11, s0, v9
	v_cvt_pk_bf16_f32 v9, v11, v11
	v_readlane_b32 s1, v3, 3
	ds_write_b16 v202, v9 offset:544
	v_readlane_b32 s0, v1, 3
	v_mul_f32_e32 v9, v128, v7
	v_mov_b32_e32 v11, s1
	v_fmac_f32_e32 v11, s0, v9
	v_cvt_pk_bf16_f32 v9, v11, v11
	v_readlane_b32 s1, v3, 4
	ds_write_b16 v202, v9 offset:816
	v_readlane_b32 s0, v1, 4
	v_mul_f32_e32 v9, v126, v7
	v_mov_b32_e32 v11, s1
	v_fmac_f32_e32 v11, s0, v9
	v_cvt_pk_bf16_f32 v9, v11, v11
	v_readlane_b32 s1, v3, 5
	ds_write_b16 v202, v9 offset:1088
	v_readlane_b32 s0, v1, 5
	v_mul_f32_e32 v9, v124, v7
	v_mov_b32_e32 v11, s1
	v_fmac_f32_e32 v11, s0, v9
	v_cvt_pk_bf16_f32 v9, v11, v11
	v_readlane_b32 s1, v3, 6
	ds_write_b16 v202, v9 offset:1360
	v_readlane_b32 s0, v1, 6
	v_mul_f32_e32 v9, v120, v7
	v_mov_b32_e32 v11, s1
	v_fmac_f32_e32 v11, s0, v9
	v_cvt_pk_bf16_f32 v9, v11, v11
	v_readlane_b32 s1, v3, 7
	ds_write_b16 v202, v9 offset:1632
	v_readlane_b32 s0, v1, 7
	v_mul_f32_e32 v9, v116, v7
	v_mov_b32_e32 v11, s1
	v_fmac_f32_e32 v11, s0, v9
	v_cvt_pk_bf16_f32 v9, v11, v11
	v_readlane_b32 s1, v3, 8
	ds_write_b16 v202, v9 offset:1904
	v_readlane_b32 s0, v1, 8
	v_mul_f32_e32 v9, v122, v7
	v_mov_b32_e32 v11, s1
; __device__ __forceinline__ bf16_t f2bf(float f) { return (bf16_t)(cvt_pk_bf16(f, f) & 0xffffu); }
; __device__ __forceinline__ void sg_item(int l, int chunk, LAS unsigned char* lds, const bf16_t* UB, const bf16_t* V2T, bf16_t* YC1, const bf16_t* Wb,
;                                         const float* sg_ln_g, const float* sg_ln_b, const float* sg_b, int lane, int wave) {
;     ...
; #pragma unroll
;         for (int c = 0; c < 64; ++c) {
;             const float gc = __uint_as_float(__builtin_amdgcn_readlane(__float_as_uint(gl), c)), bc = __uint_as_float(__builtin_amdgcn_readlane(__float_as_uint(bl), c));
;             vT[(64 * cq + c) * VS + s] = f2bf((v[c] - mean) * rstd * gc + bc);
	v_fmac_f32_e32 v11, s0, v9
	v_cvt_pk_bf16_f32 v9, v11, v11
	v_readlane_b32 s1, v3, 9
	ds_write_b16 v202, v9 offset:2176
	v_readlane_b32 s0, v1, 9
	v_mul_f32_e32 v9, v118, v7
	v_mov_b32_e32 v11, s1
	v_fmac_f32_e32 v11, s0, v9
	v_cvt_pk_bf16_f32 v9, v11, v11
	v_readlane_b32 s1, v3, 10
	ds_write_b16 v202, v9 offset:2448
	v_readlane_b32 s0, v1, 10
	v_mul_f32_e32 v9, v114, v7
	v_mov_b32_e32 v11, s1
	v_fmac_f32_e32 v11, s0, v9
	v_cvt_pk_bf16_f32 v9, v11, v11
	v_readlane_b32 s1, v3, 11
	ds_write_b16 v202, v9 offset:2720
	v_readlane_b32 s0, v1, 11
	v_mul_f32_e32 v9, v112, v7
	v_mov_b32_e32 v11, s1
	v_fmac_f32_e32 v11, s0, v9
	v_cvt_pk_bf16_f32 v9, v11, v11
	v_readlane_b32 s1, v3, 12
	ds_write_b16 v202, v9 offset:2992
	v_readlane_b32 s0, v1, 12
	v_mul_f32_e32 v9, v110, v7
	v_mov_b32_e32 v11, s1
	v_fmac_f32_e32 v11, s0, v9
	v_cvt_pk_bf16_f32 v9, v11, v11
	v_readlane_b32 s1, v3, 13
	ds_write_b16 v202, v9 offset:3264
	v_readlane_b32 s0, v1, 13
	v_mul_f32_e32 v9, v108, v7
	v_mov_b32_e32 v11, s1
	v_fmac_f32_e32 v11, s0, v9
	v_cvt_pk_bf16_f32 v9, v11, v11
	v_readlane_b32 s1, v3, 14
	ds_write_b16 v202, v9 offset:3536
	v_readlane_b32 s0, v1, 14
	v_mul_f32_e32 v9, v104, v7
	v_mov_b32_e32 v11, s1
	v_fmac_f32_e32 v11, s0, v9
	v_cvt_pk_bf16_f32 v9, v11, v11
	v_readlane_b32 s1, v3, 15
	ds_write_b16 v202, v9 offset:3808
	v_readlane_b32 s0, v1, 15
	v_mul_f32_e32 v9, v100, v7
	v_mov_b32_e32 v11, s1
	v_fmac_f32_e32 v11, s0, v9
	v_cvt_pk_bf16_f32 v9, v11, v11
	v_readlane_b32 s1, v3, 16
	ds_write_b16 v202, v9 offset:4080
	v_readlane_b32 s0, v1, 16
	v_mul_f32_e32 v9, v106, v7
	v_mov_b32_e32 v11, s1
	v_fmac_f32_e32 v11, s0, v9
	v_cvt_pk_bf16_f32 v9, v11, v11
	v_readlane_b32 s1, v3, 17
	ds_write_b16 v202, v9 offset:4352
	v_readlane_b32 s0, v1, 17
	v_mul_f32_e32 v9, v102, v7
	v_mov_b32_e32 v11, s1
	v_fmac_f32_e32 v11, s0, v9
	v_cvt_pk_bf16_f32 v9, v11, v11
	v_readlane_b32 s1, v3, 18
	ds_write_b16 v202, v9 offset:4624
	v_readlane_b32 s0, v1, 18
	v_mul_f32_e32 v9, v98, v7
	v_mov_b32_e32 v11, s1
	v_fmac_f32_e32 v11, s0, v9
	v_cvt_pk_bf16_f32 v9, v11, v11
	v_readlane_b32 s1, v3, 19
	ds_write_b16 v202, v9 offset:4896
	v_readlane_b32 s0, v1, 19
	v_mul_f32_e32 v9, v96, v7
	v_mov_b32_e32 v11, s1
	v_fmac_f32_e32 v11, s0, v9
	v_cvt_pk_bf16_f32 v9, v11, v11
	v_readlane_b32 s1, v3, 20
	ds_write_b16 v202, v9 offset:5168
	v_readlane_b32 s0, v1, 20
	v_mul_f32_e32 v9, v94, v7
	v_mov_b32_e32 v11, s1
	v_fmac_f32_e32 v11, s0, v9
	v_cvt_pk_bf16_f32 v9, v11, v11
	v_readlane_b32 s1, v3, 21
	ds_write_b16 v202, v9 offset:5440
	v_readlane_b32 s0, v1, 21
	v_mul_f32_e32 v9, v92, v7
	v_mov_b32_e32 v11, s1
	v_fmac_f32_e32 v11, s0, v9
	v_cvt_pk_bf16_f32 v9, v11, v11
	v_readlane_b32 s1, v3, 22
	ds_write_b16 v202, v9 offset:5712
	v_readlane_b32 s0, v1, 22
	v_mul_f32_e32 v9, v88, v7
	v_mov_b32_e32 v11, s1
	v_fmac_f32_e32 v11, s0, v9
	v_cvt_pk_bf16_f32 v9, v11, v11
	v_readlane_b32 s1, v3, 23
	ds_write_b16 v202, v9 offset:5984
	v_readlane_b32 s0, v1, 23
	v_mul_f32_e32 v9, v84, v7
	v_mov_b32_e32 v11, s1
	v_fmac_f32_e32 v11, s0, v9
	v_cvt_pk_bf16_f32 v9, v11, v11
	v_readlane_b32 s1, v3, 24
	ds_write_b16 v202, v9 offset:6256
	v_readlane_b32 s0, v1, 24
	v_mul_f32_e32 v9, v90, v7
	v_mov_b32_e32 v11, s1
	v_fmac_f32_e32 v11, s0, v9
	v_cvt_pk_bf16_f32 v9, v11, v11
	v_readlane_b32 s1, v3, 25
	ds_write_b16 v202, v9 offset:6528
	v_readlane_b32 s0, v1, 25
	v_mul_f32_e32 v9, v86, v7
	v_mov_b32_e32 v11, s1
	v_fmac_f32_e32 v11, s0, v9
	v_cvt_pk_bf16_f32 v9, v11, v11
	v_readlane_b32 s1, v3, 26
	ds_write_b16 v202, v9 offset:6800
	v_readlane_b32 s0, v1, 26
	v_mul_f32_e32 v9, v82, v7
	v_mov_b32_e32 v11, s1
	v_fmac_f32_e32 v11, s0, v9
	v_cvt_pk_bf16_f32 v9, v11, v11
	v_readlane_b32 s1, v3, 27
	ds_write_b16 v202, v9 offset:7072
	v_readlane_b32 s0, v1, 27
	v_mul_f32_e32 v9, v80, v7
	v_mov_b32_e32 v11, s1
	v_fmac_f32_e32 v11, s0, v9
	v_cvt_pk_bf16_f32 v9, v11, v11
	v_readlane_b32 s1, v3, 28
	ds_write_b16 v202, v9 offset:7344
	v_readlane_b32 s0, v1, 28
	v_mul_f32_e32 v9, v78, v7
	v_mov_b32_e32 v11, s1
	v_fmac_f32_e32 v11, s0, v9
	v_cvt_pk_bf16_f32 v9, v11, v11
	v_readlane_b32 s1, v3, 29
	ds_write_b16 v202, v9 offset:7616
	v_readlane_b32 s0, v1, 29
	v_mul_f32_e32 v9, v76, v7
	v_mov_b32_e32 v11, s1
	v_fmac_f32_e32 v11, s0, v9
	v_cvt_pk_bf16_f32 v9, v11, v11
	v_readlane_b32 s1, v3, 30
	ds_write_b16 v202, v9 offset:7888
	v_readlane_b32 s0, v1, 30
	v_mul_f32_e32 v9, v72, v7
	v_mov_b32_e32 v11, s1
	v_fmac_f32_e32 v11, s0, v9
	v_cvt_pk_bf16_f32 v9, v11, v11
	v_readlane_b32 s1, v3, 31
	ds_write_b16 v202, v9 offset:8160
	v_readlane_b32 s0, v1, 31
	v_mul_f32_e32 v9, v60, v7
	v_mov_b32_e32 v11, s1
	v_fmac_f32_e32 v11, s0, v9
	v_cvt_pk_bf16_f32 v9, v11, v11
	v_readlane_b32 s1, v3, 32
	ds_write_b16 v202, v9 offset:8432
	v_readlane_b32 s0, v1, 32
	v_mul_f32_e32 v9, v74, v7
	v_mov_b32_e32 v11, s1
	v_fmac_f32_e32 v11, s0, v9
	v_cvt_pk_bf16_f32 v9, v11, v11
	v_readlane_b32 s1, v3, 33
	ds_write_b16 v202, v9 offset:8704
	v_readlane_b32 s0, v1, 33
	v_mul_f32_e32 v9, v62, v7
	v_mov_b32_e32 v11, s1
	v_fmac_f32_e32 v11, s0, v9
	v_cvt_pk_bf16_f32 v9, v11, v11
	v_readlane_b32 s1, v3, 34
	ds_write_b16 v202, v9 offset:8976
	v_readlane_b32 s0, v1, 34
	v_mul_f32_e32 v9, v58, v7
	v_mov_b32_e32 v11, s1
	v_fmac_f32_e32 v11, s0, v9
	v_cvt_pk_bf16_f32 v9, v11, v11
	v_readlane_b32 s1, v3, 35
	ds_write_b16 v202, v9 offset:9248
	v_readlane_b32 s0, v1, 35
	v_mul_f32_e32 v9, v56, v7
	v_mov_b32_e32 v11, s1
	v_fmac_f32_e32 v11, s0, v9
	v_cvt_pk_bf16_f32 v9, v11, v11
	v_readlane_b32 s1, v3, 36
	ds_write_b16 v202, v9 offset:9520
	v_readlane_b32 s0, v1, 36
	v_mul_f32_e32 v9, v54, v7
	v_mov_b32_e32 v11, s1
	v_fmac_f32_e32 v11, s0, v9
	v_cvt_pk_bf16_f32 v9, v11, v11
; __device__ __forceinline__ bf16_t f2bf(float f) { return (bf16_t)(cvt_pk_bf16(f, f) & 0xffffu); }
; __device__ __forceinline__ void sg_item(int l, int chunk, LAS unsigned char* lds, const bf16_t* UB, const bf16_t* V2T, bf16_t* YC1, const bf16_t* Wb,
;                                         const float* sg_ln_g, const float* sg_ln_b, const float* sg_b, int lane, int wave) {
;     ...
; #pragma unroll
;         for (int c = 0; c < 64; ++c) {
;             const float gc = __uint_as_float(__builtin_amdgcn_readlane(__float_as_uint(gl), c)), bc = __uint_as_float(__builtin_amdgcn_readlane(__float_as_uint(bl), c));
;             vT[(64 * cq + c) * VS + s] = f2bf((v[c] - mean) * rstd * gc + bc);
;         }
;     }
;     __syncthreads();
	v_readlane_b32 s1, v3, 37
	ds_write_b16 v202, v9 offset:9792
	v_readlane_b32 s0, v1, 37
	v_mul_f32_e32 v9, v52, v7
	v_mov_b32_e32 v11, s1
	v_fmac_f32_e32 v11, s0, v9
	v_cvt_pk_bf16_f32 v9, v11, v11
	v_readlane_b32 s1, v3, 38
	ds_write_b16 v202, v9 offset:10064
	v_readlane_b32 s0, v1, 38
	v_mul_f32_e32 v9, v48, v7
	v_mov_b32_e32 v11, s1
	v_fmac_f32_e32 v11, s0, v9
	v_cvt_pk_bf16_f32 v9, v11, v11
	v_readlane_b32 s1, v3, 39
	ds_write_b16 v202, v9 offset:10336
	v_readlane_b32 s0, v1, 39
	v_mul_f32_e32 v9, v44, v7
	v_mov_b32_e32 v11, s1
	v_fmac_f32_e32 v11, s0, v9
	v_cvt_pk_bf16_f32 v9, v11, v11
	v_readlane_b32 s1, v3, 40
	ds_write_b16 v202, v9 offset:10608
	v_readlane_b32 s0, v1, 40
	v_mul_f32_e32 v9, v50, v7
	v_mov_b32_e32 v11, s1
	v_fmac_f32_e32 v11, s0, v9
	v_cvt_pk_bf16_f32 v9, v11, v11
	v_readlane_b32 s1, v3, 41
	ds_write_b16 v202, v9 offset:10880
	v_readlane_b32 s0, v1, 41
	v_mul_f32_e32 v9, v46, v7
	v_mov_b32_e32 v11, s1
	v_fmac_f32_e32 v11, s0, v9
	v_cvt_pk_bf16_f32 v9, v11, v11
	v_readlane_b32 s1, v3, 42
	ds_write_b16 v202, v9 offset:11152
	v_readlane_b32 s0, v1, 42
	v_mul_f32_e32 v9, v42, v7
	v_mov_b32_e32 v11, s1
	v_fmac_f32_e32 v11, s0, v9
	v_cvt_pk_bf16_f32 v9, v11, v11
	v_readlane_b32 s1, v3, 43
	ds_write_b16 v202, v9 offset:11424
	v_readlane_b32 s0, v1, 43
	v_mul_f32_e32 v9, v40, v7
	v_mov_b32_e32 v11, s1
	v_fmac_f32_e32 v11, s0, v9
	v_cvt_pk_bf16_f32 v9, v11, v11
	v_readlane_b32 s1, v3, 44
	ds_write_b16 v202, v9 offset:11696
	v_readlane_b32 s0, v1, 44
	v_mul_f32_e32 v9, v38, v7
	v_mov_b32_e32 v11, s1
	v_fmac_f32_e32 v11, s0, v9
	v_cvt_pk_bf16_f32 v9, v11, v11
	v_readlane_b32 s1, v3, 45
	ds_write_b16 v202, v9 offset:11968
	v_readlane_b32 s0, v1, 45
	v_mul_f32_e32 v9, v36, v7
	v_mov_b32_e32 v11, s1
	v_fmac_f32_e32 v11, s0, v9
	v_cvt_pk_bf16_f32 v9, v11, v11
	v_readlane_b32 s1, v3, 46
	ds_write_b16 v202, v9 offset:12240
	v_readlane_b32 s0, v1, 46
	v_mul_f32_e32 v9, v32, v7
	v_mov_b32_e32 v11, s1
	v_fmac_f32_e32 v11, s0, v9
	v_cvt_pk_bf16_f32 v9, v11, v11
	v_readlane_b32 s1, v3, 47
	ds_write_b16 v202, v9 offset:12512
	v_readlane_b32 s0, v1, 47
	v_mul_f32_e32 v9, v28, v7
	v_mov_b32_e32 v11, s1
	v_fmac_f32_e32 v11, s0, v9
	v_cvt_pk_bf16_f32 v9, v11, v11
	v_readlane_b32 s1, v3, 48
	ds_write_b16 v202, v9 offset:12784
	v_readlane_b32 s0, v1, 48
	v_mul_f32_e32 v9, v34, v7
	v_mov_b32_e32 v11, s1
	v_fmac_f32_e32 v11, s0, v9
	v_cvt_pk_bf16_f32 v9, v11, v11
	v_readlane_b32 s1, v3, 49
	ds_write_b16 v202, v9 offset:13056
	v_readlane_b32 s0, v1, 49
	v_mul_f32_e32 v9, v30, v7
	v_mov_b32_e32 v11, s1
	v_fmac_f32_e32 v11, s0, v9
	v_cvt_pk_bf16_f32 v9, v11, v11
	v_readlane_b32 s1, v3, 50
	v_fmac_f32_e32 v26, 0xbb800000, v5
	ds_write_b16 v202, v9 offset:13328
	v_readlane_b32 s0, v1, 50
	v_mul_f32_e32 v9, v26, v7
	v_mov_b32_e32 v11, s1
	v_fmac_f32_e32 v11, s0, v9
	v_cvt_pk_bf16_f32 v9, v11, v11
	v_readlane_b32 s1, v3, 51
	v_fmac_f32_e32 v24, 0xbb800000, v5
	ds_write_b16 v202, v9 offset:13600
	v_readlane_b32 s0, v1, 51
	v_mul_f32_e32 v9, v24, v7
	v_mov_b32_e32 v11, s1
	v_fmac_f32_e32 v11, s0, v9
	v_cvt_pk_bf16_f32 v9, v11, v11
	v_readlane_b32 s1, v3, 52
	v_fmac_f32_e32 v22, 0xbb800000, v5
	ds_write_b16 v202, v9 offset:13872
	v_readlane_b32 s0, v1, 52
	v_mul_f32_e32 v9, v22, v7
	v_mov_b32_e32 v11, s1
	v_fmac_f32_e32 v11, s0, v9
	v_cvt_pk_bf16_f32 v9, v11, v11
	v_readlane_b32 s1, v3, 53
	v_fmac_f32_e32 v20, 0xbb800000, v5
	ds_write_b16 v202, v9 offset:14144
	v_readlane_b32 s0, v1, 53
	v_mul_f32_e32 v9, v20, v7
	v_mov_b32_e32 v11, s1
	v_fmac_f32_e32 v11, s0, v9
	v_cvt_pk_bf16_f32 v9, v11, v11
	v_readlane_b32 s1, v3, 54
	v_fmac_f32_e32 v16, 0xbb800000, v5
	ds_write_b16 v202, v9 offset:14416
	v_readlane_b32 s0, v1, 54
	v_mul_f32_e32 v9, v16, v7
	v_mov_b32_e32 v11, s1
	v_fmac_f32_e32 v11, s0, v9
	v_cvt_pk_bf16_f32 v9, v11, v11
	v_readlane_b32 s1, v3, 55
	v_fmac_f32_e32 v12, 0xbb800000, v5
	ds_write_b16 v202, v9 offset:14688
	v_readlane_b32 s0, v1, 55
	v_mul_f32_e32 v9, v12, v7
	v_mov_b32_e32 v11, s1
	v_fmac_f32_e32 v11, s0, v9
	v_cvt_pk_bf16_f32 v9, v11, v11
	v_readlane_b32 s1, v3, 56
	v_fmac_f32_e32 v18, 0xbb800000, v5
	ds_write_b16 v202, v9 offset:14960
	v_readlane_b32 s0, v1, 56
	v_mul_f32_e32 v9, v18, v7
	v_mov_b32_e32 v11, s1
	v_fmac_f32_e32 v11, s0, v9
	v_cvt_pk_bf16_f32 v9, v11, v11
	v_readlane_b32 s1, v3, 57
	v_fmac_f32_e32 v14, 0xbb800000, v5
	ds_write_b16 v202, v9 offset:15232
	v_readlane_b32 s0, v1, 57
	v_mul_f32_e32 v9, v14, v7
	v_mov_b32_e32 v11, s1
	v_fmac_f32_e32 v11, s0, v9
	v_cvt_pk_bf16_f32 v9, v11, v11
	v_readlane_b32 s1, v3, 58
	v_fmac_f32_e32 v10, 0xbb800000, v5
	ds_write_b16 v202, v9 offset:15504
	v_readlane_b32 s0, v1, 58
	v_mul_f32_e32 v9, v10, v7
	v_mov_b32_e32 v10, s1
	v_fmac_f32_e32 v10, s0, v9
	v_cvt_pk_bf16_f32 v9, v10, v10
	v_readlane_b32 s1, v3, 59
	v_fmac_f32_e32 v8, 0xbb800000, v5
	ds_write_b16 v202, v9 offset:15776
	v_readlane_b32 s0, v1, 59
	v_mul_f32_e32 v8, v8, v7
	v_mov_b32_e32 v9, s1
	v_fmac_f32_e32 v9, s0, v8
	v_cvt_pk_bf16_f32 v8, v9, v9
	v_readlane_b32 s1, v3, 60
	v_fmac_f32_e32 v6, 0xbb800000, v5
	ds_write_b16 v202, v8 offset:16048
	v_readlane_b32 s0, v1, 60
	v_mul_f32_e32 v6, v6, v7
	v_mov_b32_e32 v8, s1
	v_fmac_f32_e32 v8, s0, v6
	v_cvt_pk_bf16_f32 v6, v8, v8
	v_readlane_b32 s1, v3, 61
	v_fmac_f32_e32 v4, 0xbb800000, v5
	ds_write_b16 v202, v6 offset:16320
	v_readlane_b32 s0, v1, 61
	v_mul_f32_e32 v4, v4, v7
	v_mov_b32_e32 v6, s1
	v_fmac_f32_e32 v6, s0, v4
	v_cvt_pk_bf16_f32 v4, v6, v6
	v_readlane_b32 s1, v3, 62
	v_fmac_f32_e32 v2, 0xbb800000, v5
	ds_write_b16 v202, v4 offset:16592
	v_readlane_b32 s0, v1, 62
	v_mul_f32_e32 v2, v2, v7
	v_mov_b32_e32 v4, s1
	v_readlane_b32 s1, v3, 63
	v_fmac_f32_e32 v0, 0xbb800000, v5
	v_fmac_f32_e32 v4, s0, v2
	v_readlane_b32 s0, v1, 63
	v_mul_f32_e32 v0, v0, v7
	v_mov_b32_e32 v1, s1
	v_cvt_pk_bf16_f32 v2, v4, v4
	ds_write_b16 v202, v2 offset:16864
	v_fmac_f32_e32 v1, s0, v0
	v_cvt_pk_bf16_f32 v0, v1, v1
	ds_write_b16 v202, v0 offset:17136
	s_waitcnt lgkmcnt(0)
	s_barrier
; #define LAS __attribute__((address_space(3)))
; __device__ __forceinline__ bf16_t f2bf(float f) { return (bf16_t)(cvt_pk_bf16(f, f) & 0xffffu); }
; __device__ __forceinline__ int crow(int r, int hi) { return (r & 3) + 8 * (r >> 2) + 4 * hi; }
; __device__ __forceinline__ void sg_item(int l, int chunk, LAS unsigned char* lds, const bf16_t* UB, const bf16_t* V2T, bf16_t* YC1, const bf16_t* Wb,
;                                         const float* sg_ln_g, const float* sg_ln_b, const float* sg_b, int lane, int wave) {
;     ...
;         bf16x8 Bf[8];
; #pragma unroll
;         for (int ks = 0; ks < 8; ++ks) Bf[ks] = *(const LAS bf16x8*)(vT + c * VS + 16 * ks + 8 * hi);
; #pragma unroll
;         for (int i = 0; i < 4; ++i) {
; #pragma unroll
;             for (int kb = 0; kb < 2 * i + 2; kb += 4) {
;                 u32x4 af[4]; const void* pp[4];
; #pragma unroll
;                 for (int j = 0; j < 4; ++j) pp[j] = Wg + (size_t)(32 * i) * 128 + 16 * ((kb + j) < 2 * i + 2 ? (kb + j) : 0);
;                 ld_b128_s4(af, avoff, pp);
; #pragma unroll
;                 for (int j = 0; j < 4; ++j) if (kb + j < 2 * i + 2) acc[i] = __builtin_amdgcn_mfma_f32_32x32x16_bf16(__builtin_bit_cast(bf16x8, af[j]), Bf[kb + j], acc[i], 0, 0, 0);
;             }
;         }
;         const float sb_lo = sg_b[(l * 4 + g) * 128 + lane], sb_hi = sg_b[(l * 4 + g) * 128 + 64 + lane];
;         const unsigned uvoff = (unsigned)(4 * hi * BW + c) * 2u;
; #pragma unroll
;         for (int i = 0; i < 4; ++i) {
;             unsigned uu[16];
; #pragma unroll
;             for (int rb = 0; rb < 16; rb += 8) {
;                 unsigned raw[8]; const void* pp[8];
; #pragma unroll
;                 for (int j = 0; j < 8; ++j) pp[j] = UB + (r0 + 32 * i + crow(rb + j, 0)) * BW;
;                 ld_u16_s8(raw, uvoff, pp);
; #pragma unroll
;                 for (int j = 0; j < 8; ++j) uu[rb + j] = raw[j];
;             }
; #pragma unroll
;             for (int r = 0; r < 16; ++r) {
;                 const int t = 32 * i + crow(r, hi);
;                 const float sbv = __int_as_float(__builtin_amdgcn_ds_bpermute((t & 63) << 2, __float_as_int(i < 2 ? sb_lo : sb_hi)));
;                 YC1[(r0 + t) * BW + c] = f2bf(__uint_as_float(uu[r] << 16) * (acc[i][r] + sbv));
	ds_read_b128 v[0:3], v201
	ds_read_b128 v[72:75], v201 offset:32
	ds_read_b128 v[76:79], v201 offset:64
	ds_read_b128 v[80:83], v201 offset:96
	ds_read_b128 v[84:87], v201 offset:128
	ds_read_b128 v[88:91], v201 offset:160
	ds_read_b128 v[92:95], v201 offset:192
	ds_read_b128 v[96:99], v201 offset:224
	s_nop 4
	global_load_dwordx4 v[4:7], v203, s[6:7]
	global_load_dwordx4 v[8:11], v203, s[8:9]
	global_load_dwordx4 v[12:15], v203, s[6:7]
	global_load_dwordx4 v[16:19], v203, s[6:7]
	s_waitcnt vmcnt(0)
	s_add_u32 s0, s92, s80
	s_waitcnt lgkmcnt(7)
	v_mfma_f32_32x32x16_bf16 v[48:63], v[4:7], v[0:3], 0
	s_addc_u32 s1, s93, s81
	s_add_u32 s50, s0, 0x200
	s_addc_u32 s51, s1, 0
	s_add_u32 s52, s0, 0x400
	s_addc_u32 s53, s1, 0
	s_add_u32 s54, s0, 0x600
	s_addc_u32 s55, s1, 0
	s_waitcnt lgkmcnt(6)
	v_mfma_f32_32x32x16_bf16 v[48:63], v[8:11], v[72:75], v[48:63]
	s_nop 4
	global_load_dwordx4 v[4:7], v203, s[10:11]
	global_load_dwordx4 v[8:11], v203, s[16:17]
	global_load_dwordx4 v[12:15], v203, s[18:19]
	global_load_dwordx4 v[16:19], v203, s[20:21]
	s_waitcnt vmcnt(0)
	s_add_u32 s56, s0, 0x1000
	s_addc_u32 s57, s1, 0
	s_add_u32 s58, s0, 0x1200
	s_addc_u32 s59, s1, 0
	s_add_u32 s60, s0, 0x1400
	s_addc_u32 s61, s1, 0
	v_mfma_f32_32x32x16_bf16 v[32:47], v[4:7], v[0:3], 0
	s_add_u32 s62, s0, 0x1600
	s_addc_u32 s63, s1, 0
	v_mfma_f32_32x32x16_bf16 v[32:47], v[8:11], v[72:75], v[32:47]
	s_waitcnt lgkmcnt(5)
	v_mfma_f32_32x32x16_bf16 v[32:47], v[12:15], v[76:79], v[32:47]
	s_nop 4
	global_load_dwordx4 v[4:7], v203, s[22:23]
	global_load_dwordx4 v[8:11], v203, s[24:25]
	global_load_dwordx4 v[12:15], v203, s[26:27]
	global_load_dwordx4 v[100:103], v203, s[28:29]
	s_waitcnt vmcnt(0)
	s_waitcnt lgkmcnt(4)
	v_mfma_f32_32x32x16_bf16 v[32:47], v[16:19], v[80:83], v[32:47]
	v_mfma_f32_32x32x16_bf16 v[16:31], v[4:7], v[0:3], 0
	v_mfma_f32_32x32x16_bf16 v[16:31], v[8:11], v[72:75], v[16:31]
	v_mfma_f32_32x32x16_bf16 v[16:31], v[12:15], v[76:79], v[16:31]
	v_mfma_f32_32x32x16_bf16 v[16:31], v[100:103], v[80:83], v[16:31]
	s_nop 4
	global_load_dwordx4 v[4:7], v203, s[30:31]
	global_load_dwordx4 v[8:11], v203, s[34:35]
	global_load_dwordx4 v[12:15], v203, s[22:23]
	global_load_dwordx4 v[100:103], v203, s[22:23]
	s_waitcnt vmcnt(0)
	s_waitcnt lgkmcnt(3)
	v_mfma_f32_32x32x16_bf16 v[16:31], v[4:7], v[84:87], v[16:31]
	s_nop 4
	global_load_dwordx4 v[4:7], v203, s[36:37]
	global_load_dwordx4 v[100:103], v203, s[38:39]
	global_load_dwordx4 v[104:107], v203, s[68:69]
	global_load_dwordx4 v[108:111], v203, s[70:71]
	s_waitcnt vmcnt(0)
	s_waitcnt lgkmcnt(2)
	v_mfma_f32_32x32x16_bf16 v[16:31], v[8:11], v[88:91], v[16:31]
	v_mfma_f32_32x32x16_bf16 v[0:15], v[4:7], v[0:3], 0
	v_mfma_f32_32x32x16_bf16 v[0:15], v[100:103], v[72:75], v[0:15]
	v_mfma_f32_32x32x16_bf16 v[0:15], v[104:107], v[76:79], v[0:15]
	v_mfma_f32_32x32x16_bf16 v[0:15], v[108:111], v[80:83], v[0:15]
	s_nop 4
	global_load_dwordx4 v[72:75], v203, s[72:73]
	global_load_dwordx4 v[76:79], v203, s[74:75]
	global_load_dwordx4 v[80:83], v203, s[76:77]
	global_load_dwordx4 v[100:103], v203, s[78:79]
	s_waitcnt vmcnt(0)
	s_nop 0
	v_mfma_f32_32x32x16_bf16 v[0:15], v[72:75], v[84:87], v[0:15]
	global_load_dword v75, v[68:69], off
	global_load_dword v74, v[68:69], off offset:256
	s_waitcnt vmcnt(1)
	ds_bpermute_b32 v73, v200, v75
	v_mfma_f32_32x32x16_bf16 v[0:15], v[76:79], v[88:91], v[0:15]
	s_waitcnt lgkmcnt(0)
	v_add_f32_e32 v48, v48, v73
	v_mfma_f32_32x32x16_bf16 v[0:15], v[80:83], v[92:95], v[0:15]
	s_nop 4
	global_load_ushort v72, v152, s[48:49]
	global_load_ushort v90, v152, s[50:51]
	global_load_ushort v89, v152, s[52:53]
	global_load_ushort v88, v152, s[54:55]
	global_load_ushort v87, v152, s[56:57]
	global_load_ushort v86, v152, s[58:59]
	global_load_ushort v84, v152, s[60:61]
	global_load_ushort v83, v152, s[62:63]
	s_waitcnt vmcnt(0)
	s_add_u32 s48, s0, 0x2000
	s_addc_u32 s49, s1, 0
	s_add_u32 s50, s0, 0x2200
	s_addc_u32 s51, s1, 0
	s_add_u32 s52, s0, 0x2400
	s_addc_u32 s53, s1, 0
	s_add_u32 s54, s0, 0x2600
	s_addc_u32 s55, s1, 0
	s_add_u32 s56, s0, 0x3000
	s_addc_u32 s57, s1, 0
	s_add_u32 s58, s0, 0x3200
	v_lshlrev_b32_e32 v72, 16, v72
	s_addc_u32 s59, s1, 0
	v_mul_f32_e32 v48, v48, v72
	v_lshl_add_u64 v[72:73], v[70:71], 0, s[80:81]
	s_add_u32 s60, s0, 0x3400
	v_add_co_u32_e32 v92, vcc, s12, v72
	s_addc_u32 s61, s1, 0
	s_nop 0
	v_addc_co_u32_e32 v93, vcc, 0, v73, vcc
	s_mov_b32 s12, 0xb401000
	s_add_u32 s62, s0, 0x3600
	v_add_co_u32_e32 v94, vcc, s12, v72
	s_addc_u32 s63, s1, 0
	s_nop 4
	global_load_ushort v85, v152, s[48:49]
	global_load_ushort v82, v152, s[50:51]
	global_load_ushort v81, v152, s[52:53]
	global_load_ushort v80, v152, s[54:55]
	global_load_ushort v79, v152, s[56:57]
	global_load_ushort v78, v152, s[58:59]
	global_load_ushort v77, v152, s[60:61]
	global_load_ushort v76, v152, s[62:63]
	s_waitcnt vmcnt(0)
	v_cvt_pk_bf16_f32 v48, v48, v48
	s_nop 0
	v_addc_co_u32_e32 v95, vcc, 0, v73, vcc
	global_store_short v[94:95], v48, off offset:-4096
	ds_bpermute_b32 v48, v204, v75
	v_lshlrev_b32_e32 v90, 16, v90
	s_mov_b32 s12, 0xb402000
	s_add_u32 s48, s0, 0x4000
	s_addc_u32 s49, s1, 0
	s_waitcnt lgkmcnt(0)
	v_add_f32_e32 v48, v49, v48
	v_mul_f32_e32 v48, v48, v90
	v_cvt_pk_bf16_f32 v48, v48, v48
	global_store_short v[92:93], v48, off offset:512
	ds_bpermute_b32 v48, v205, v75
	v_lshlrev_b32_e32 v49, 16, v89
	s_add_u32 s50, s0, 0x4200
	s_addc_u32 s51, s1, 0
	s_add_u32 s52, s0, 0x4400
	s_waitcnt lgkmcnt(0)
	v_add_f32_e32 v48, v50, v48
	v_mul_f32_e32 v48, v48, v49
	v_cvt_pk_bf16_f32 v48, v48, v48
	global_store_short v[92:93], v48, off offset:1024
	ds_bpermute_b32 v48, v206, v75
	v_lshlrev_b32_e32 v49, 16, v88
	s_addc_u32 s53, s1, 0
	s_add_u32 s54, s0, 0x4600
	s_addc_u32 s55, s1, 0
	s_waitcnt lgkmcnt(0)
; __device__ __forceinline__ bf16_t f2bf(float f) { return (bf16_t)(cvt_pk_bf16(f, f) & 0xffffu); }
; __device__ __forceinline__ int crow(int r, int hi) { return (r & 3) + 8 * (r >> 2) + 4 * hi; }
; __device__ __forceinline__ void sg_item(int l, int chunk, LAS unsigned char* lds, const bf16_t* UB, const bf16_t* V2T, bf16_t* YC1, const bf16_t* Wb,
;                                         const float* sg_ln_g, const float* sg_ln_b, const float* sg_b, int lane, int wave) {
;     ...
; #pragma unroll
;         for (int i = 0; i < 4; ++i) {
;             unsigned uu[16];
; #pragma unroll
;             for (int rb = 0; rb < 16; rb += 8) {
;                 unsigned raw[8]; const void* pp[8];
; #pragma unroll
;                 for (int j = 0; j < 8; ++j) pp[j] = UB + (r0 + 32 * i + crow(rb + j, 0)) * BW;
;                 ld_u16_s8(raw, uvoff, pp);
; #pragma unroll
;                 for (int j = 0; j < 8; ++j) uu[rb + j] = raw[j];
;             }
; #pragma unroll
;             for (int r = 0; r < 16; ++r) {
;                 const int t = 32 * i + crow(r, hi);
;                 const float sbv = __int_as_float(__builtin_amdgcn_ds_bpermute((t & 63) << 2, __float_as_int(i < 2 ? sb_lo : sb_hi)));
;                 YC1[(r0 + t) * BW + c] = f2bf(__uint_as_float(uu[r] << 16) * (acc[i][r] + sbv));
	v_add_f32_e32 v48, v51, v48
	v_mul_f32_e32 v48, v48, v49
	v_cvt_pk_bf16_f32 v48, v48, v48
	global_store_short v[92:93], v48, off offset:1536
	ds_bpermute_b32 v48, v207, v75
	v_lshlrev_b32_e32 v49, 16, v87
	s_add_u32 s56, s0, 0x5000
	s_addc_u32 s57, s1, 0
	s_add_u32 s58, s0, 0x5200
	s_waitcnt lgkmcnt(0)
	v_add_f32_e32 v48, v52, v48
	v_mul_f32_e32 v48, v48, v49
	v_cvt_pk_bf16_f32 v48, v48, v48
	global_store_short v[94:95], v48, off
	ds_bpermute_b32 v48, v208, v75
	v_lshlrev_b32_e32 v49, 16, v86
	s_addc_u32 s59, s1, 0
	s_add_u32 s60, s0, 0x5400
	s_addc_u32 s61, s1, 0
	s_waitcnt lgkmcnt(0)
	v_add_f32_e32 v48, v53, v48
	v_mul_f32_e32 v48, v48, v49
	v_cvt_pk_bf16_f32 v48, v48, v48
	global_store_short v[94:95], v48, off offset:512
	ds_bpermute_b32 v48, v209, v75
	v_lshlrev_b32_e32 v49, 16, v84
	v_lshlrev_b32_e32 v53, 16, v82
	s_add_u32 s62, s0, 0x5600
	s_addc_u32 s63, s1, 0
	s_waitcnt lgkmcnt(0)
	v_add_f32_e32 v48, v54, v48
	v_mul_f32_e32 v48, v48, v49
	v_cvt_pk_bf16_f32 v48, v48, v48
	global_store_short v[94:95], v48, off offset:1024
	ds_bpermute_b32 v48, v210, v75
	v_lshlrev_b32_e32 v49, 16, v83
	v_mfma_f32_32x32x16_bf16 v[0:15], v[100:103], v[96:99], v[0:15]
	v_lshl_add_u64 v[70:71], v[70:71], 0, s[82:83]
	s_waitcnt lgkmcnt(0)
	v_add_f32_e32 v48, v55, v48
	v_mul_f32_e32 v48, v48, v49
	v_cvt_pk_bf16_f32 v48, v48, v48
	global_store_short v[94:95], v48, off offset:1536
	ds_bpermute_b32 v48, v211, v75
	v_lshlrev_b32_e32 v49, 16, v85
	s_waitcnt lgkmcnt(0)
	v_add_f32_e32 v48, v56, v48
	v_mul_f32_e32 v48, v48, v49
	v_cvt_pk_bf16_f32 v52, v48, v48
	v_add_co_u32_e32 v48, vcc, s12, v72
	s_mov_b32 s12, 0xb403000
	s_nop 0
	v_addc_co_u32_e32 v49, vcc, 0, v73, vcc
	v_add_co_u32_e32 v50, vcc, s12, v72
	s_mov_b32 s12, 0xb404000
	s_nop 0
	v_addc_co_u32_e32 v51, vcc, 0, v73, vcc
	global_store_short v[50:51], v52, off offset:-4096
	ds_bpermute_b32 v52, v212, v75
	s_waitcnt lgkmcnt(0)
	v_add_f32_e32 v52, v57, v52
	v_mul_f32_e32 v52, v52, v53
	v_cvt_pk_bf16_f32 v52, v52, v52
	global_store_short v[48:49], v52, off offset:512
	ds_bpermute_b32 v52, v213, v75
	v_lshlrev_b32_e32 v53, 16, v81
	s_waitcnt lgkmcnt(0)
	v_add_f32_e32 v52, v58, v52
	v_mul_f32_e32 v52, v52, v53
	v_cvt_pk_bf16_f32 v52, v52, v52
	global_store_short v[48:49], v52, off offset:1024
	ds_bpermute_b32 v52, v214, v75
	v_lshlrev_b32_e32 v53, 16, v80
	s_waitcnt lgkmcnt(0)
	v_add_f32_e32 v52, v59, v52
	v_mul_f32_e32 v52, v52, v53
	v_cvt_pk_bf16_f32 v52, v52, v52
	global_store_short v[48:49], v52, off offset:1536
	ds_bpermute_b32 v48, v215, v75
	v_lshlrev_b32_e32 v49, 16, v79
	s_waitcnt lgkmcnt(0)
	v_add_f32_e32 v48, v60, v48
	v_mul_f32_e32 v48, v48, v49
	v_cvt_pk_bf16_f32 v48, v48, v48
	global_store_short v[50:51], v48, off
	ds_bpermute_b32 v48, v216, v75
	v_lshlrev_b32_e32 v49, 16, v78
	s_waitcnt lgkmcnt(0)
	v_add_f32_e32 v48, v61, v48
	v_mul_f32_e32 v48, v48, v49
	v_cvt_pk_bf16_f32 v48, v48, v48
	global_store_short v[50:51], v48, off offset:512
	ds_bpermute_b32 v48, v217, v75
	v_lshlrev_b32_e32 v49, 16, v77
	s_waitcnt lgkmcnt(0)
	v_add_f32_e32 v48, v62, v48
	v_mul_f32_e32 v48, v48, v49
	v_cvt_pk_bf16_f32 v48, v48, v48
	global_store_short v[50:51], v48, off offset:1024
	ds_bpermute_b32 v48, v218, v75
	v_lshlrev_b32_e32 v49, 16, v76
	ds_bpermute_b32 v76, v153, v75
	s_waitcnt lgkmcnt(1)
	v_add_f32_e32 v48, v63, v48
	v_mul_f32_e32 v48, v48, v49
	v_cvt_pk_bf16_f32 v48, v48, v48
	global_store_short v[50:51], v48, off offset:1536
	s_nop 4
	global_load_ushort v63, v152, s[48:49]
	global_load_ushort v62, v152, s[50:51]
	global_load_ushort v61, v152, s[52:53]
	global_load_ushort v60, v152, s[54:55]
	global_load_ushort v59, v152, s[56:57]
	global_load_ushort v58, v152, s[58:59]
	global_load_ushort v56, v152, s[60:61]
	global_load_ushort v55, v152, s[62:63]
	s_waitcnt vmcnt(0)
	s_add_u32 s48, s0, 0x6000
	s_addc_u32 s49, s1, 0
	s_add_u32 s50, s0, 0x6200
	s_addc_u32 s51, s1, 0
	s_add_u32 s52, s0, 0x6400
	s_addc_u32 s53, s1, 0
	s_add_u32 s54, s0, 0x6600
	s_addc_u32 s55, s1, 0
	s_add_u32 s56, s0, 0x7000
	s_addc_u32 s57, s1, 0
	s_add_u32 s58, s0, 0x7200
	s_addc_u32 s59, s1, 0
	s_add_u32 s60, s0, 0x7400
	s_waitcnt lgkmcnt(0)
	v_add_f32_e32 v32, v32, v76
	v_add_co_u32_e32 v76, vcc, s12, v72
	s_addc_u32 s61, s1, 0
	v_lshlrev_b32_e32 v63, 16, v63
	v_addc_co_u32_e32 v77, vcc, 0, v73, vcc
	s_mov_b32 s12, 0xb405000
	s_add_u32 s62, s0, 0x7600
	v_mul_f32_e32 v32, v32, v63
	v_add_co_u32_e32 v78, vcc, s12, v72
	s_addc_u32 s63, s1, 0
	s_nop 4
	global_load_ushort v57, v152, s[48:49]
	global_load_ushort v54, v152, s[50:51]
	global_load_ushort v53, v152, s[52:53]
	global_load_ushort v52, v152, s[54:55]
	global_load_ushort v51, v152, s[56:57]
	global_load_ushort v50, v152, s[58:59]
	global_load_ushort v49, v152, s[60:61]
	global_load_ushort v48, v152, s[62:63]
	s_waitcnt vmcnt(0)
	v_cvt_pk_bf16_f32 v32, v32, v32
	s_nop 0
	v_addc_co_u32_e32 v79, vcc, 0, v73, vcc
	global_store_short v[78:79], v32, off offset:-4096
	ds_bpermute_b32 v32, v154, v75
	v_lshlrev_b32_e32 v62, 16, v62
	s_mov_b32 s12, 0xb406000
	s_add_u32 s48, s0, 0x8000
	s_addc_u32 s49, s1, 0
	s_waitcnt lgkmcnt(0)
	v_add_f32_e32 v32, v33, v32
	v_mul_f32_e32 v32, v32, v62
	v_cvt_pk_bf16_f32 v32, v32, v32
	global_store_short v[76:77], v32, off offset:512
	ds_bpermute_b32 v32, v155, v75
	v_lshlrev_b32_e32 v33, 16, v61
	s_add_u32 s50, s0, 0x8200
	s_addc_u32 s51, s1, 0
	s_add_u32 s52, s0, 0x8400
	s_waitcnt lgkmcnt(0)
	v_add_f32_e32 v32, v34, v32
	v_mul_f32_e32 v32, v32, v33
	v_cvt_pk_bf16_f32 v32, v32, v32
	global_store_short v[76:77], v32, off offset:1024
	ds_bpermute_b32 v32, v157, v75
	v_lshlrev_b32_e32 v33, 16, v60
	s_addc_u32 s53, s1, 0
	s_add_u32 s54, s0, 0x8600
	s_addc_u32 s55, s1, 0
	s_waitcnt lgkmcnt(0)
; __device__ __forceinline__ bf16_t f2bf(float f) { return (bf16_t)(cvt_pk_bf16(f, f) & 0xffffu); }
; __device__ __forceinline__ int crow(int r, int hi) { return (r & 3) + 8 * (r >> 2) + 4 * hi; }
; __device__ __forceinline__ void sg_item(int l, int chunk, LAS unsigned char* lds, const bf16_t* UB, const bf16_t* V2T, bf16_t* YC1, const bf16_t* Wb,
;                                         const float* sg_ln_g, const float* sg_ln_b, const float* sg_b, int lane, int wave) {
;     ...
; #pragma unroll
;         for (int i = 0; i < 4; ++i) {
;             unsigned uu[16];
; #pragma unroll
;             for (int rb = 0; rb < 16; rb += 8) {
;                 unsigned raw[8]; const void* pp[8];
; #pragma unroll
;                 for (int j = 0; j < 8; ++j) pp[j] = UB + (r0 + 32 * i + crow(rb + j, 0)) * BW;
;                 ld_u16_s8(raw, uvoff, pp);
; #pragma unroll
;                 for (int j = 0; j < 8; ++j) uu[rb + j] = raw[j];
;             }
; #pragma unroll
;             for (int r = 0; r < 16; ++r) {
;                 const int t = 32 * i + crow(r, hi);
;                 const float sbv = __int_as_float(__builtin_amdgcn_ds_bpermute((t & 63) << 2, __float_as_int(i < 2 ? sb_lo : sb_hi)));
;                 YC1[(r0 + t) * BW + c] = f2bf(__uint_as_float(uu[r] << 16) * (acc[i][r] + sbv));
	v_add_f32_e32 v32, v35, v32
	v_mul_f32_e32 v32, v32, v33
	v_cvt_pk_bf16_f32 v32, v32, v32
	global_store_short v[76:77], v32, off offset:1536
	ds_bpermute_b32 v32, v161, v75
	v_lshlrev_b32_e32 v33, 16, v59
	s_add_u32 s56, s0, 0x9000
	s_addc_u32 s57, s1, 0
	s_add_u32 s58, s0, 0x9200
	s_waitcnt lgkmcnt(0)
	v_add_f32_e32 v32, v36, v32
	v_mul_f32_e32 v32, v32, v33
	v_cvt_pk_bf16_f32 v32, v32, v32
	global_store_short v[78:79], v32, off
	ds_bpermute_b32 v32, v162, v75
	v_lshlrev_b32_e32 v33, 16, v58
	s_addc_u32 s59, s1, 0
	s_add_u32 s60, s0, 0x9400
	s_addc_u32 s61, s1, 0
	s_waitcnt lgkmcnt(0)
	v_add_f32_e32 v32, v37, v32
	v_mul_f32_e32 v32, v32, v33
	v_cvt_pk_bf16_f32 v32, v32, v32
	global_store_short v[78:79], v32, off offset:512
	ds_bpermute_b32 v32, v163, v75
	v_lshlrev_b32_e32 v33, 16, v56
	v_lshlrev_b32_e32 v37, 16, v54
	s_add_u32 s62, s0, 0x9600
	s_addc_u32 s63, s1, 0
	s_waitcnt lgkmcnt(0)
	v_add_f32_e32 v32, v38, v32
	v_mul_f32_e32 v32, v32, v33
	v_cvt_pk_bf16_f32 v32, v32, v32
	global_store_short v[78:79], v32, off offset:1024
	ds_bpermute_b32 v32, v164, v75
	v_lshlrev_b32_e32 v33, 16, v55
	s_waitcnt lgkmcnt(0)
	v_add_f32_e32 v32, v39, v32
	v_mul_f32_e32 v32, v32, v33
	v_cvt_pk_bf16_f32 v32, v32, v32
	global_store_short v[78:79], v32, off offset:1536
	ds_bpermute_b32 v32, v165, v75
	v_lshlrev_b32_e32 v33, 16, v57
	s_waitcnt lgkmcnt(0)
	v_add_f32_e32 v32, v40, v32
	v_mul_f32_e32 v32, v32, v33
	v_cvt_pk_bf16_f32 v36, v32, v32
	v_add_co_u32_e32 v32, vcc, s12, v72
	s_mov_b32 s12, 0xb407000
	s_nop 0
	v_addc_co_u32_e32 v33, vcc, 0, v73, vcc
	v_add_co_u32_e32 v34, vcc, s12, v72
	s_mov_b32 s12, 0xb408000
	s_nop 0
	v_addc_co_u32_e32 v35, vcc, 0, v73, vcc
	global_store_short v[34:35], v36, off offset:-4096
	ds_bpermute_b32 v36, v166, v75
	s_waitcnt lgkmcnt(0)
	v_add_f32_e32 v36, v41, v36
	v_mul_f32_e32 v36, v36, v37
	v_cvt_pk_bf16_f32 v36, v36, v36
	global_store_short v[32:33], v36, off offset:512
	ds_bpermute_b32 v36, v167, v75
	v_lshlrev_b32_e32 v37, 16, v53
	s_waitcnt lgkmcnt(0)
	v_add_f32_e32 v36, v42, v36
	v_mul_f32_e32 v36, v36, v37
	v_cvt_pk_bf16_f32 v36, v36, v36
	global_store_short v[32:33], v36, off offset:1024
	ds_bpermute_b32 v36, v168, v75
	v_lshlrev_b32_e32 v37, 16, v52
	s_waitcnt lgkmcnt(0)
	v_add_f32_e32 v36, v43, v36
	v_mul_f32_e32 v36, v36, v37
	v_cvt_pk_bf16_f32 v36, v36, v36
	global_store_short v[32:33], v36, off offset:1536
	ds_bpermute_b32 v32, v169, v75
	v_lshlrev_b32_e32 v33, 16, v51
	s_waitcnt lgkmcnt(0)
	v_add_f32_e32 v32, v44, v32
	v_mul_f32_e32 v32, v32, v33
	v_cvt_pk_bf16_f32 v32, v32, v32
	global_store_short v[34:35], v32, off
	ds_bpermute_b32 v32, v170, v75
	v_lshlrev_b32_e32 v33, 16, v50
	s_waitcnt lgkmcnt(0)
	v_add_f32_e32 v32, v45, v32
	v_mul_f32_e32 v32, v32, v33
	v_cvt_pk_bf16_f32 v32, v32, v32
	global_store_short v[34:35], v32, off offset:512
	ds_bpermute_b32 v32, v171, v75
	v_lshlrev_b32_e32 v33, 16, v49
	s_waitcnt lgkmcnt(0)
	v_add_f32_e32 v32, v46, v32
	v_mul_f32_e32 v32, v32, v33
	v_cvt_pk_bf16_f32 v32, v32, v32
	global_store_short v[34:35], v32, off offset:1024
	ds_bpermute_b32 v32, v172, v75
	v_lshlrev_b32_e32 v33, 16, v48
	s_waitcnt vmcnt(31)
	ds_bpermute_b32 v48, v200, v74
	s_waitcnt lgkmcnt(1)
	v_add_f32_e32 v32, v47, v32
	v_mul_f32_e32 v32, v32, v33
	v_cvt_pk_bf16_f32 v32, v32, v32
	global_store_short v[34:35], v32, off offset:1536
	s_nop 4
	global_load_ushort v47, v152, s[48:49]
	global_load_ushort v46, v152, s[50:51]
	global_load_ushort v45, v152, s[52:53]
	global_load_ushort v44, v152, s[54:55]
	global_load_ushort v43, v152, s[56:57]
	global_load_ushort v42, v152, s[58:59]
	global_load_ushort v40, v152, s[60:61]
	global_load_ushort v39, v152, s[62:63]
	s_waitcnt vmcnt(0)
	s_add_u32 s48, s0, 0xa000
	s_addc_u32 s49, s1, 0
	s_add_u32 s50, s0, 0xa200
	s_addc_u32 s51, s1, 0
	s_add_u32 s52, s0, 0xa400
	s_addc_u32 s53, s1, 0
	s_add_u32 s54, s0, 0xa600
	s_addc_u32 s55, s1, 0
	s_add_u32 s56, s0, 0xb000
	s_addc_u32 s57, s1, 0
	s_add_u32 s58, s0, 0xb200
	s_addc_u32 s59, s1, 0
	s_add_u32 s60, s0, 0xb400
	s_waitcnt lgkmcnt(0)
	v_add_f32_e32 v16, v16, v48
	v_add_co_u32_e32 v48, vcc, s12, v72
	s_addc_u32 s61, s1, 0
	v_lshlrev_b32_e32 v47, 16, v47
	v_addc_co_u32_e32 v49, vcc, 0, v73, vcc
	s_mov_b32 s12, 0xb409000
	s_add_u32 s62, s0, 0xb600
	v_mul_f32_e32 v16, v16, v47
	v_add_co_u32_e32 v50, vcc, s12, v72
	s_addc_u32 s63, s1, 0
	s_nop 4
	global_load_ushort v41, v152, s[48:49]
	global_load_ushort v38, v152, s[50:51]
	global_load_ushort v37, v152, s[52:53]
	global_load_ushort v36, v152, s[54:55]
	global_load_ushort v35, v152, s[56:57]
	global_load_ushort v34, v152, s[58:59]
	global_load_ushort v33, v152, s[60:61]
	global_load_ushort v32, v152, s[62:63]
	s_waitcnt vmcnt(0)
	v_cvt_pk_bf16_f32 v16, v16, v16
	s_nop 0
	v_addc_co_u32_e32 v51, vcc, 0, v73, vcc
	global_store_short v[50:51], v16, off offset:-4096
	ds_bpermute_b32 v16, v173, v74
	v_lshlrev_b32_e32 v46, 16, v46
	s_mov_b32 s12, 0xb40a000
	s_add_u32 s48, s0, 0xc000
	s_addc_u32 s49, s1, 0
	s_waitcnt lgkmcnt(0)
	v_add_f32_e32 v16, v17, v16
	v_mul_f32_e32 v16, v16, v46
	v_cvt_pk_bf16_f32 v16, v16, v16
	global_store_short v[48:49], v16, off offset:512
	ds_bpermute_b32 v16, v174, v74
	v_lshlrev_b32_e32 v17, 16, v45
	s_add_u32 s50, s0, 0xc200
	s_addc_u32 s51, s1, 0
	s_add_u32 s52, s0, 0xc400
	s_waitcnt lgkmcnt(0)
	v_add_f32_e32 v16, v18, v16
	v_mul_f32_e32 v16, v16, v17
	v_cvt_pk_bf16_f32 v16, v16, v16
	global_store_short v[48:49], v16, off offset:1024
	ds_bpermute_b32 v16, v175, v74
	v_lshlrev_b32_e32 v17, 16, v44
	s_addc_u32 s53, s1, 0
	s_add_u32 s54, s0, 0xc600
	s_addc_u32 s55, s1, 0
	s_waitcnt lgkmcnt(0)
; __device__ __forceinline__ bf16_t f2bf(float f) { return (bf16_t)(cvt_pk_bf16(f, f) & 0xffffu); }
; __device__ __forceinline__ int crow(int r, int hi) { return (r & 3) + 8 * (r >> 2) + 4 * hi; }
; __device__ __forceinline__ void sg_item(int l, int chunk, LAS unsigned char* lds, const bf16_t* UB, const bf16_t* V2T, bf16_t* YC1, const bf16_t* Wb,
;                                         const float* sg_ln_g, const float* sg_ln_b, const float* sg_b, int lane, int wave) {
;     ...
; #pragma unroll
;         for (int i = 0; i < 4; ++i) {
;             unsigned uu[16];
; #pragma unroll
;             for (int rb = 0; rb < 16; rb += 8) {
;                 unsigned raw[8]; const void* pp[8];
; #pragma unroll
;                 for (int j = 0; j < 8; ++j) pp[j] = UB + (r0 + 32 * i + crow(rb + j, 0)) * BW;
;                 ld_u16_s8(raw, uvoff, pp);
; #pragma unroll
;                 for (int j = 0; j < 8; ++j) uu[rb + j] = raw[j];
;             }
; #pragma unroll
;             for (int r = 0; r < 16; ++r) {
;                 const int t = 32 * i + crow(r, hi);
;                 const float sbv = __int_as_float(__builtin_amdgcn_ds_bpermute((t & 63) << 2, __float_as_int(i < 2 ? sb_lo : sb_hi)));
;                 YC1[(r0 + t) * BW + c] = f2bf(__uint_as_float(uu[r] << 16) * (acc[i][r] + sbv));
	v_add_f32_e32 v16, v19, v16
	v_mul_f32_e32 v16, v16, v17
	v_cvt_pk_bf16_f32 v16, v16, v16
	global_store_short v[48:49], v16, off offset:1536
	ds_bpermute_b32 v16, v176, v74
	v_lshlrev_b32_e32 v17, 16, v43
	s_add_u32 s56, s0, 0xd000
	s_addc_u32 s57, s1, 0
	s_add_u32 s58, s0, 0xd200
	s_waitcnt lgkmcnt(0)
	v_add_f32_e32 v16, v20, v16
	v_mul_f32_e32 v16, v16, v17
	v_cvt_pk_bf16_f32 v16, v16, v16
	global_store_short v[50:51], v16, off
	ds_bpermute_b32 v16, v177, v74
	v_lshlrev_b32_e32 v17, 16, v42
	s_addc_u32 s59, s1, 0
	s_add_u32 s60, s0, 0xd400
	s_addc_u32 s61, s1, 0
	s_waitcnt lgkmcnt(0)
	v_add_f32_e32 v16, v21, v16
	v_mul_f32_e32 v16, v16, v17
	v_cvt_pk_bf16_f32 v16, v16, v16
	global_store_short v[50:51], v16, off offset:512
	ds_bpermute_b32 v16, v178, v74
	v_lshlrev_b32_e32 v17, 16, v40
	v_lshlrev_b32_e32 v21, 16, v38
	s_add_u32 s62, s0, 0xd600
	s_addc_u32 s63, s1, 0
	s_waitcnt lgkmcnt(0)
	v_add_f32_e32 v16, v22, v16
	v_mul_f32_e32 v16, v16, v17
	v_cvt_pk_bf16_f32 v16, v16, v16
	global_store_short v[50:51], v16, off offset:1024
	ds_bpermute_b32 v16, v179, v74
	v_lshlrev_b32_e32 v17, 16, v39
	s_waitcnt lgkmcnt(0)
	v_add_f32_e32 v16, v23, v16
	v_mul_f32_e32 v16, v16, v17
	v_cvt_pk_bf16_f32 v16, v16, v16
	global_store_short v[50:51], v16, off offset:1536
	ds_bpermute_b32 v16, v180, v74
	v_lshlrev_b32_e32 v17, 16, v41
	s_waitcnt lgkmcnt(0)
	v_add_f32_e32 v16, v24, v16
	v_mul_f32_e32 v16, v16, v17
	v_cvt_pk_bf16_f32 v20, v16, v16
	v_add_co_u32_e32 v16, vcc, s12, v72
	s_mov_b32 s12, 0xb40b000
	s_nop 0
	v_addc_co_u32_e32 v17, vcc, 0, v73, vcc
	v_add_co_u32_e32 v18, vcc, s12, v72
	s_nop 1
	v_addc_co_u32_e32 v19, vcc, 0, v73, vcc
	global_store_short v[18:19], v20, off offset:-4096
	ds_bpermute_b32 v20, v181, v74
	s_waitcnt lgkmcnt(0)
	v_add_f32_e32 v20, v25, v20
	v_mul_f32_e32 v20, v20, v21
	v_cvt_pk_bf16_f32 v20, v20, v20
	global_store_short v[16:17], v20, off offset:512
	ds_bpermute_b32 v20, v182, v74
	v_lshlrev_b32_e32 v21, 16, v37
	s_waitcnt lgkmcnt(0)
	v_add_f32_e32 v20, v26, v20
	v_mul_f32_e32 v20, v20, v21
	v_cvt_pk_bf16_f32 v20, v20, v20
	global_store_short v[16:17], v20, off offset:1024
	ds_bpermute_b32 v20, v183, v74
	v_lshlrev_b32_e32 v21, 16, v36
	s_waitcnt lgkmcnt(0)
	v_add_f32_e32 v20, v27, v20
	v_mul_f32_e32 v20, v20, v21
	v_cvt_pk_bf16_f32 v20, v20, v20
	global_store_short v[16:17], v20, off offset:1536
	ds_bpermute_b32 v16, v184, v74
	v_lshlrev_b32_e32 v17, 16, v35
	s_waitcnt lgkmcnt(0)
	v_add_f32_e32 v16, v28, v16
	v_mul_f32_e32 v16, v16, v17
	v_cvt_pk_bf16_f32 v16, v16, v16
	global_store_short v[18:19], v16, off
	ds_bpermute_b32 v16, v185, v74
	v_lshlrev_b32_e32 v17, 16, v34
	s_waitcnt lgkmcnt(0)
	v_add_f32_e32 v16, v29, v16
	v_mul_f32_e32 v16, v16, v17
	v_cvt_pk_bf16_f32 v16, v16, v16
	global_store_short v[18:19], v16, off offset:512
	ds_bpermute_b32 v16, v186, v74
	v_lshlrev_b32_e32 v17, 16, v33
	s_waitcnt lgkmcnt(0)
	v_add_f32_e32 v16, v30, v16
	v_mul_f32_e32 v16, v16, v17
	v_cvt_pk_bf16_f32 v16, v16, v16
	global_store_short v[18:19], v16, off offset:1024
	ds_bpermute_b32 v16, v187, v74
	v_lshlrev_b32_e32 v17, 16, v32
	ds_bpermute_b32 v32, v188, v74
	s_waitcnt lgkmcnt(1)
	v_add_f32_e32 v16, v31, v16
	v_mul_f32_e32 v16, v16, v17
	v_cvt_pk_bf16_f32 v16, v16, v16
	global_store_short v[18:19], v16, off offset:1536
	s_nop 4
	global_load_ushort v31, v152, s[48:49]
	global_load_ushort v30, v152, s[50:51]
	global_load_ushort v29, v152, s[52:53]
	global_load_ushort v28, v152, s[54:55]
	global_load_ushort v27, v152, s[56:57]
	global_load_ushort v26, v152, s[58:59]
	global_load_ushort v24, v152, s[60:61]
	global_load_ushort v23, v152, s[62:63]
	s_waitcnt vmcnt(0)
	s_add_u32 s48, s0, 0xe000
	s_addc_u32 s49, s1, 0
	s_add_u32 s50, s0, 0xe200
	s_addc_u32 s51, s1, 0
	s_add_u32 s52, s0, 0xe400
	s_addc_u32 s53, s1, 0
	s_add_u32 s54, s0, 0xe600
	s_addc_u32 s55, s1, 0
	s_add_u32 s56, s0, 0xf000
	s_addc_u32 s57, s1, 0
	s_add_u32 s58, s0, 0xf200
	s_addc_u32 s59, s1, 0
	s_add_u32 s60, s0, 0xf400
	s_addc_u32 s61, s1, 0
	s_add_u32 s0, s0, 0xf600
	s_addc_u32 s1, s1, 0
	s_nop 4
	global_load_ushort v25, v152, s[48:49]
	global_load_ushort v22, v152, s[50:51]
	global_load_ushort v21, v152, s[52:53]
	global_load_ushort v20, v152, s[54:55]
	global_load_ushort v19, v152, s[56:57]
	global_load_ushort v18, v152, s[58:59]
	global_load_ushort v17, v152, s[60:61]
	global_load_ushort v16, v152, s[0:1]
	s_waitcnt vmcnt(0)
; __device__ __forceinline__ bf16_t f2bf(float f) { return (bf16_t)(cvt_pk_bf16(f, f) & 0xffffu); }
; __device__ __forceinline__ int crow(int r, int hi) { return (r & 3) + 8 * (r >> 2) + 4 * hi; }
; __device__ __forceinline__ void sg_item(int l, int chunk, LAS unsigned char* lds, const bf16_t* UB, const bf16_t* V2T, bf16_t* YC1, const bf16_t* Wb,
;                                         const float* sg_ln_g, const float* sg_ln_b, const float* sg_b, int lane, int wave) {
;     ...
; #pragma unroll
;         for (int i = 0; i < 4; ++i) {
;             unsigned uu[16];
; #pragma unroll
;             for (int rb = 0; rb < 16; rb += 8) {
;                 unsigned raw[8]; const void* pp[8];
; #pragma unroll
;                 for (int j = 0; j < 8; ++j) pp[j] = UB + (r0 + 32 * i + crow(rb + j, 0)) * BW;
;                 ld_u16_s8(raw, uvoff, pp);
; #pragma unroll
;                 for (int j = 0; j < 8; ++j) uu[rb + j] = raw[j];
;             }
; #pragma unroll
;             for (int r = 0; r < 16; ++r) {
;                 const int t = 32 * i + crow(r, hi);
;                 const float sbv = __int_as_float(__builtin_amdgcn_ds_bpermute((t & 63) << 2, __float_as_int(i < 2 ? sb_lo : sb_hi)));
;                 YC1[(r0 + t) * BW + c] = f2bf(__uint_as_float(uu[r] << 16) * (acc[i][r] + sbv));
;             }
;         }
;     }
;     __syncthreads();
; __global__ void __launch_bounds__(512, 2) __attribute__((amdgpu_waves_per_eu(2, 2))) mk_fwd(Args a_) {
;     ...
;                 for (int it = vcu; it < MTOK / 128; it += G) sg_item(l, it, lds, UB, V2B, YC + (size_t)MTOK * BW, (const bf16_t*)(ws + WS_SGW) + (size_t)l * 4 * 128 * 128, a.in[10], a.in[11], a.in[13], lane, wave);
	s_mov_b32 s0, 0xb40c000
	s_waitcnt lgkmcnt(0)
	v_add_f32_e32 v0, v0, v32
	v_add_co_u32_e32 v32, vcc, s0, v72
	v_lshlrev_b32_e32 v31, 16, v31
	s_nop 0
	v_addc_co_u32_e32 v33, vcc, 0, v73, vcc
	s_mov_b32 s0, 0xb40d000
	v_mul_f32_e32 v0, v0, v31
	v_add_co_u32_e32 v34, vcc, s0, v72
	v_cvt_pk_bf16_f32 v0, v0, v0
	v_lshlrev_b32_e32 v30, 16, v30
	s_nop 0
	v_addc_co_u32_e32 v35, vcc, 0, v73, vcc
	global_store_short v[34:35], v0, off offset:-4096
	ds_bpermute_b32 v0, v189, v74
	s_mov_b32 s0, 0xb40e000
	s_add_i32 s13, s13, s96
	s_add_u32 s92, s92, s82
	s_addc_u32 s93, s93, s83
	s_waitcnt lgkmcnt(0)
	v_add_f32_e32 v0, v1, v0
	v_mul_f32_e32 v0, v0, v30
	v_cvt_pk_bf16_f32 v0, v0, v0
	global_store_short v[32:33], v0, off offset:512
	ds_bpermute_b32 v0, v190, v74
	v_lshlrev_b32_e32 v1, 16, v29
	s_add_u32 s4, s4, s82
	s_addc_u32 s5, s5, s83
	s_add_u32 s84, s84, s86
	s_waitcnt lgkmcnt(0)
	v_add_f32_e32 v0, v2, v0
	v_mul_f32_e32 v0, v0, v1
	v_cvt_pk_bf16_f32 v0, v0, v0
	global_store_short v[32:33], v0, off offset:1024
	ds_bpermute_b32 v0, v157, v74
	v_lshlrev_b32_e32 v1, 16, v28
	s_addc_u32 s85, s85, s87
	s_add_u32 s88, s88, s90
	s_addc_u32 s89, s89, s91
	s_waitcnt lgkmcnt(0)
	v_add_f32_e32 v0, v3, v0
	v_mul_f32_e32 v0, v0, v1
	v_cvt_pk_bf16_f32 v0, v0, v0
	global_store_short v[32:33], v0, off offset:1536
	ds_bpermute_b32 v0, v191, v74
	v_lshlrev_b32_e32 v1, 16, v27
	v_lshlrev_b32_e32 v3, 16, v22
	s_cmpk_gt_i32 s13, 0xff
	s_waitcnt lgkmcnt(0)
	v_add_f32_e32 v0, v4, v0
	v_mul_f32_e32 v0, v0, v1
	v_cvt_pk_bf16_f32 v0, v0, v0
	global_store_short v[34:35], v0, off
	ds_bpermute_b32 v0, v192, v74
	v_lshlrev_b32_e32 v1, 16, v26
	s_waitcnt lgkmcnt(0)
	v_add_f32_e32 v0, v5, v0
	v_mul_f32_e32 v0, v0, v1
	v_cvt_pk_bf16_f32 v0, v0, v0
	global_store_short v[34:35], v0, off offset:512
	ds_bpermute_b32 v0, v193, v74
	v_lshlrev_b32_e32 v1, 16, v24
	s_waitcnt lgkmcnt(0)
	v_add_f32_e32 v0, v6, v0
	v_mul_f32_e32 v0, v0, v1
	v_cvt_pk_bf16_f32 v0, v0, v0
	global_store_short v[34:35], v0, off offset:1024
	ds_bpermute_b32 v0, v164, v74
	v_lshlrev_b32_e32 v1, 16, v23
	s_waitcnt lgkmcnt(0)
	v_add_f32_e32 v0, v7, v0
	v_mul_f32_e32 v0, v0, v1
	v_cvt_pk_bf16_f32 v0, v0, v0
	global_store_short v[34:35], v0, off offset:1536
	ds_bpermute_b32 v0, v194, v74
	v_lshlrev_b32_e32 v1, 16, v25
	s_waitcnt lgkmcnt(0)
	v_add_f32_e32 v0, v8, v0
	v_mul_f32_e32 v0, v0, v1
	v_cvt_pk_bf16_f32 v2, v0, v0
	v_add_co_u32_e32 v0, vcc, s0, v72
	s_mov_b32 s0, 0xb40f000
	s_nop 0
	v_addc_co_u32_e32 v1, vcc, 0, v73, vcc
	v_add_co_u32_e32 v4, vcc, s0, v72
	s_nop 1
	v_addc_co_u32_e32 v5, vcc, 0, v73, vcc
	global_store_short v[4:5], v2, off offset:-4096
	ds_bpermute_b32 v2, v195, v74
	s_waitcnt lgkmcnt(0)
	v_add_f32_e32 v2, v9, v2
	v_mul_f32_e32 v2, v2, v3
	v_cvt_pk_bf16_f32 v2, v2, v2
	global_store_short v[0:1], v2, off offset:512
	ds_bpermute_b32 v2, v196, v74
	v_lshlrev_b32_e32 v3, 16, v21
	s_waitcnt lgkmcnt(0)
	v_add_f32_e32 v2, v10, v2
	v_mul_f32_e32 v2, v2, v3
	v_cvt_pk_bf16_f32 v2, v2, v2
	global_store_short v[0:1], v2, off offset:1024
	ds_bpermute_b32 v2, v168, v74
	v_lshlrev_b32_e32 v3, 16, v20
	s_waitcnt lgkmcnt(0)
	v_add_f32_e32 v2, v11, v2
	v_mul_f32_e32 v2, v2, v3
	v_cvt_pk_bf16_f32 v2, v2, v2
	global_store_short v[0:1], v2, off offset:1536
	ds_bpermute_b32 v0, v197, v74
	v_lshlrev_b32_e32 v1, 16, v19
	s_waitcnt lgkmcnt(0)
	v_add_f32_e32 v0, v12, v0
	v_mul_f32_e32 v0, v0, v1
	v_cvt_pk_bf16_f32 v0, v0, v0
	global_store_short v[4:5], v0, off
	ds_bpermute_b32 v0, v198, v74
	v_lshlrev_b32_e32 v1, 16, v18
	s_waitcnt lgkmcnt(0)
	v_add_f32_e32 v0, v13, v0
	v_mul_f32_e32 v0, v0, v1
	v_cvt_pk_bf16_f32 v0, v0, v0
	global_store_short v[4:5], v0, off offset:512
	ds_bpermute_b32 v0, v199, v74
	v_lshlrev_b32_e32 v1, 16, v17
	s_waitcnt lgkmcnt(0)
	v_add_f32_e32 v0, v14, v0
	v_mul_f32_e32 v0, v0, v1
	v_cvt_pk_bf16_f32 v0, v0, v0
	global_store_short v[4:5], v0, off offset:1024
	ds_bpermute_b32 v0, v172, v74
	v_lshlrev_b32_e32 v1, 16, v16
	s_waitcnt lgkmcnt(0)
	v_add_f32_e32 v0, v15, v0
	v_mul_f32_e32 v0, v0, v1
	v_cvt_pk_bf16_f32 v0, v0, v0
	global_store_short v[4:5], v0, off offset:1536
	s_waitcnt vmcnt(63) expcnt(7) lgkmcnt(15)
	s_barrier
	s_cbranch_scc0 .LBB0_79
